# all GEMM K-loops: raise wave priority before the pre-MMA barrier instead of after it (MMA wave wakes at prio 1)
# baseline (speedup 1.0000x reference)
; #define PG8_STAGE(bufoff, gbase, voff) do { _Pragma("unroll") for (int _i = 0; _i < 2; ++_i) \
;         __builtin_amdgcn_global_load_lds((const unsigned*)((const char*)(gbase) + (voff)[_i]), (PG8_LAS unsigned*)(lds + (bufoff) + ldsw + _i * 8192), 16, 0, 0); } while (0)
; #define PG8_LDA(dst, b, h) do { _Pragma("unroll") for (int m = 0; m < 4; ++m) _Pragma("unroll") for (int k = 0; k < 2; ++k) dst[m][k] = *(const PG8_LAS bf16x8*)(lds + PG8_SA(b, h) + aoff + m * 2048 + k * 1024); } while (0)
; #define PG8_LDB(dst, b, h) do { _Pragma("unroll") for (int n = 0; n < 2; ++n) _Pragma("unroll") for (int k = 0; k < 2; ++k) dst[n][k] = *(const PG8_LAS bf16x8*)(lds + PG8_SB(b, h) + boff + n * 2048 + k * 1024); } while (0)
; #define PG8_MMA(ai, bj, At, Bt) do { __builtin_amdgcn_s_setprio(1); _Pragma("unroll") for (int m = 0; m < 4; ++m) _Pragma("unroll") for (int n = 0; n < 2; ++n) _Pragma("unroll") for (int k = 0; k < 2; ++k) \
;         acc[ai][bj][m][n] = __builtin_amdgcn_mfma_f32_16x16x32_bf16(Bt[n][k], At[m][k], acc[ai][bj][m][n], 0, 0, 0); __builtin_amdgcn_s_setprio(0); } while (0)
; #define PG8_WAIT_V(n) asm volatile("s_waitcnt vmcnt(" #n ")" ::: "memory")
; #define PG8_WAIT_L(n) asm volatile("s_waitcnt lgkmcnt(" #n ")" ::: "memory")
; #define PG8_BAR __builtin_amdgcn_s_barrier()
; #define PG8_SCHED __builtin_amdgcn_sched_barrier(0)
; template <class Epi, class Sched, bool ALIGN_EPI = false, bool SP2 = false>
; __device__ __forceinline__ void gemm_phase(PG8_LAS unsigned char* lds, const Gemm g, const Sched& S, const Epi& E) {
;     ...
;             PG8_LDB(B0, 0, 0); PG8_LDB(B1, 0, 1); PG8_SCHED; PG8_LDA(At, 0, 0); PG8_STAGE(PG8_SA(1, 1), a1 + hstep, voffA);
;             PG8_WAIT_V(8); PG8_WAIT_L(0); PG8_BAR; PG8_MMA(0, 0, At, B0); PG8_MMA(0, 1, At, B1); PG8_BAR; PG8_SCHED;
;             PG8_LDA(At, 0, 1); PG8_STAGE(PG8_SB(0, 0), b2, voffB); PG8_STAGE(PG8_SB(0, 1), b2 + hstep, voffB); PG8_STAGE(PG8_SA(0, 0), a2, voffA);
;             PG8_WAIT_V(8); PG8_WAIT_L(0); PG8_BAR; PG8_MMA(1, 0, At, B0); PG8_MMA(1, 1, At, B1); PG8_BAR; PG8_SCHED;
.LBB0_57:
	s_add_u32 s46, s44, 0xfff80080
	s_addc_u32 s47, s45, -1
	s_add_i32 s57, 0, 0x10000
	s_cmp_eq_u32 s56, 28
	s_cselect_b32 s49, s17, s47
	s_cselect_b32 s48, s25, s46
	v_add_u32_e32 v148, s57, v151
	s_cselect_b32 s47, s15, s55
	s_cselect_b32 s46, s43, s54
	s_add_i32 s60, 0, 0x14000
	ds_read_b128 v[140:143], v148
	ds_read_b128 v[144:147], v148 offset:1024
	ds_read_b128 v[174:177], v148 offset:2048
	ds_read_b128 v[178:181], v148 offset:3072
	v_add_u32_e32 v148, s60, v151
	ds_read_b128 v[182:185], v148
	ds_read_b128 v[186:189], v148 offset:1024
	ds_read_b128 v[190:193], v148 offset:2048
	ds_read_b128 v[194:197], v148 offset:3072
	v_lshl_add_u64 v[148:149], s[44:45], 0, v[136:137]
	s_add_i32 m0, s28, 0xc000
	ds_read_b128 v[198:201], v172
	ds_read_b128 v[202:205], v172 offset:1024
	ds_read_b128 v[206:209], v172 offset:2048
	ds_read_b128 v[210:213], v172 offset:3072
	ds_read_b128 v[220:223], v172 offset:4096
	ds_read_b128 v[224:227], v172 offset:5120
	ds_read_b128 v[228:231], v172 offset:6144
	ds_read_b128 v[232:235], v172 offset:7168
	global_load_lds_dwordx4 v[148:149], off
	v_lshl_add_u64 v[148:149], s[44:45], 0, v[138:139]
	s_add_i32 m0, s28, 0xe000
	s_nop 0
	global_load_lds_dwordx4 v[148:149], off
	s_waitcnt vmcnt(8)
	s_waitcnt lgkmcnt(0)
	s_setprio 1
	s_barrier
	s_waitcnt lgkmcnt(0)
	v_mfma_f32_16x16x32_bf16 v[124:127], v[140:143], v[198:201], v[124:127]
	v_mfma_f32_16x16x32_bf16 v[120:123], v[174:177], v[198:201], v[120:123]
	v_mfma_f32_16x16x32_bf16 v[116:119], v[140:143], v[206:209], v[116:119]
	v_mfma_f32_16x16x32_bf16 v[112:115], v[174:177], v[206:209], v[112:115]
	v_mfma_f32_16x16x32_bf16 v[100:103], v[140:143], v[220:223], v[100:103]
	v_mfma_f32_16x16x32_bf16 v[96:99], v[174:177], v[220:223], v[96:99]
	v_mfma_f32_16x16x32_bf16 v[84:87], v[140:143], v[228:231], v[84:87]
	v_mfma_f32_16x16x32_bf16 v[80:83], v[174:177], v[228:231], v[80:83]
	v_mfma_f32_16x16x32_bf16 v[124:127], v[144:147], v[202:205], v[124:127]
	v_mfma_f32_16x16x32_bf16 v[120:123], v[178:181], v[202:205], v[120:123]
	v_mfma_f32_16x16x32_bf16 v[116:119], v[144:147], v[210:213], v[116:119]
	v_mfma_f32_16x16x32_bf16 v[112:115], v[178:181], v[210:213], v[112:115]
	v_mfma_f32_16x16x32_bf16 v[100:103], v[144:147], v[224:227], v[100:103]
	v_mfma_f32_16x16x32_bf16 v[96:99], v[178:181], v[224:227], v[96:99]
	v_mfma_f32_16x16x32_bf16 v[84:87], v[144:147], v[232:235], v[84:87]
	v_mfma_f32_16x16x32_bf16 v[80:83], v[178:181], v[232:235], v[80:83]
	s_setprio 0
	s_setprio 1
	v_mfma_f32_16x16x32_bf16 v[108:111], v[182:185], v[198:201], v[108:111]
	v_mfma_f32_16x16x32_bf16 v[104:107], v[190:193], v[198:201], v[104:107]
	v_mfma_f32_16x16x32_bf16 v[92:95], v[182:185], v[206:209], v[92:95]
	v_mfma_f32_16x16x32_bf16 v[88:91], v[190:193], v[206:209], v[88:91]
	v_mfma_f32_16x16x32_bf16 v[76:79], v[182:185], v[220:223], v[76:79]
	v_mfma_f32_16x16x32_bf16 v[72:75], v[190:193], v[220:223], v[72:75]
	v_mfma_f32_16x16x32_bf16 v[68:71], v[182:185], v[228:231], v[68:71]
	v_mfma_f32_16x16x32_bf16 v[64:67], v[190:193], v[228:231], v[64:67]
	v_mfma_f32_16x16x32_bf16 v[108:111], v[186:189], v[202:205], v[108:111]
	v_mfma_f32_16x16x32_bf16 v[104:107], v[194:197], v[202:205], v[104:107]
	v_mfma_f32_16x16x32_bf16 v[92:95], v[186:189], v[210:213], v[92:95]
	v_mfma_f32_16x16x32_bf16 v[88:91], v[194:197], v[210:213], v[88:91]
	v_mfma_f32_16x16x32_bf16 v[76:79], v[186:189], v[224:227], v[76:79]
	v_mfma_f32_16x16x32_bf16 v[72:75], v[194:197], v[224:227], v[72:75]
	v_mfma_f32_16x16x32_bf16 v[68:71], v[186:189], v[232:235], v[68:71]
	v_mfma_f32_16x16x32_bf16 v[64:67], v[194:197], v[232:235], v[64:67]
	s_setprio 0
	s_barrier
	s_add_i32 s57, s57, s26
	v_lshl_add_u64 v[148:149], s[46:47], 0, v[132:133]
	s_mov_b32 m0, s57
	ds_read_b128 v[198:201], v172 offset:16384
	ds_read_b128 v[202:205], v172 offset:17408
	ds_read_b128 v[206:209], v172 offset:18432
	ds_read_b128 v[210:213], v172 offset:19456
	ds_read_b128 v[220:223], v172 offset:20480
	ds_read_b128 v[224:227], v172 offset:21504
	ds_read_b128 v[228:231], v172 offset:22528
	ds_read_b128 v[232:235], v172 offset:23552
	global_load_lds_dwordx4 v[148:149], off
	s_add_i32 m0, s57, 0x2000
	s_add_u32 s58, s46, 0x80000
	v_lshl_add_u64 v[214:215], s[46:47], 0, v[128:129]
	s_addc_u32 s59, s47, 0
	s_add_i32 s57, s60, s26
	global_load_lds_dwordx4 v[214:215], off
	v_lshl_add_u64 v[236:237], s[58:59], 0, v[132:133]
	s_mov_b32 m0, s57
	v_lshl_add_u64 v[238:239], s[48:49], 0, v[130:131]
	global_load_lds_dwordx4 v[236:237], off
	v_lshl_add_u64 v[236:237], s[58:59], 0, v[128:129]
	s_add_i32 m0, s57, 0x2000
	s_nop 0
	global_load_lds_dwordx4 v[236:237], off
	v_lshl_add_u64 v[236:237], s[48:49], 0, v[134:135]
	s_mov_b32 m0, s28
	s_nop 0
	global_load_lds_dwordx4 v[236:237], off
	s_mov_b32 m0, s29
	s_nop 0
	global_load_lds_dwordx4 v[238:239], off
	s_waitcnt vmcnt(8)
	s_waitcnt lgkmcnt(0)
	s_setprio 1
	s_barrier
; #define PG8_STAGE(bufoff, gbase, voff) do { _Pragma("unroll") for (int _i = 0; _i < 2; ++_i) \
;         __builtin_amdgcn_global_load_lds((const unsigned*)((const char*)(gbase) + (voff)[_i]), (PG8_LAS unsigned*)(lds + (bufoff) + ldsw + _i * 8192), 16, 0, 0); } while (0)
; #define PG8_LDA(dst, b, h) do { _Pragma("unroll") for (int m = 0; m < 4; ++m) _Pragma("unroll") for (int k = 0; k < 2; ++k) dst[m][k] = *(const PG8_LAS bf16x8*)(lds + PG8_SA(b, h) + aoff + m * 2048 + k * 1024); } while (0)
; #define PG8_LDB(dst, b, h) do { _Pragma("unroll") for (int n = 0; n < 2; ++n) _Pragma("unroll") for (int k = 0; k < 2; ++k) dst[n][k] = *(const PG8_LAS bf16x8*)(lds + PG8_SB(b, h) + boff + n * 2048 + k * 1024); } while (0)
; #define PG8_MMA(ai, bj, At, Bt) do { __builtin_amdgcn_s_setprio(1); _Pragma("unroll") for (int m = 0; m < 4; ++m) _Pragma("unroll") for (int n = 0; n < 2; ++n) _Pragma("unroll") for (int k = 0; k < 2; ++k) \
;         acc[ai][bj][m][n] = __builtin_amdgcn_mfma_f32_16x16x32_bf16(Bt[n][k], At[m][k], acc[ai][bj][m][n], 0, 0, 0); __builtin_amdgcn_s_setprio(0); } while (0)
; #define PG8_WAIT_V(n) asm volatile("s_waitcnt vmcnt(" #n ")" ::: "memory")
; #define PG8_WAIT_L(n) asm volatile("s_waitcnt lgkmcnt(" #n ")" ::: "memory")
; #define PG8_BAR __builtin_amdgcn_s_barrier()
; #define PG8_SCHED __builtin_amdgcn_sched_barrier(0)
; template <class Epi, class Sched, bool ALIGN_EPI = false, bool SP2 = false>
; __device__ __forceinline__ void gemm_phase(PG8_LAS unsigned char* lds, const Gemm g, const Sched& S, const Epi& E) {
;     ...
;             PG8_WAIT_V(8); PG8_WAIT_L(0); PG8_BAR; PG8_MMA(1, 0, At, B0); PG8_MMA(1, 1, At, B1); PG8_BAR; PG8_SCHED;
;             PG8_LDB(B0, 1, 0); PG8_LDB(B1, 1, 1); PG8_SCHED; PG8_LDA(At, 1, 0); PG8_STAGE(PG8_SA(0, 1), a2 + hstep, voffA);
;             PG8_WAIT_V(8); PG8_WAIT_L(0); PG8_BAR; PG8_MMA(0, 0, At, B0); PG8_MMA(0, 1, At, B1); PG8_BAR; PG8_SCHED;
	s_waitcnt lgkmcnt(0)
	v_mfma_f32_16x16x32_bf16 v[60:63], v[140:143], v[198:201], v[60:63]
	v_mfma_f32_16x16x32_bf16 v[56:59], v[174:177], v[198:201], v[56:59]
	v_mfma_f32_16x16x32_bf16 v[52:55], v[140:143], v[206:209], v[52:55]
	v_mfma_f32_16x16x32_bf16 v[48:51], v[174:177], v[206:209], v[48:51]
	v_mfma_f32_16x16x32_bf16 v[36:39], v[140:143], v[220:223], v[36:39]
	v_mfma_f32_16x16x32_bf16 v[32:35], v[174:177], v[220:223], v[32:35]
	v_mfma_f32_16x16x32_bf16 v[20:23], v[140:143], v[228:231], v[20:23]
	v_mfma_f32_16x16x32_bf16 v[16:19], v[174:177], v[228:231], v[16:19]
	v_mfma_f32_16x16x32_bf16 v[60:63], v[144:147], v[202:205], v[60:63]
	v_mfma_f32_16x16x32_bf16 v[56:59], v[178:181], v[202:205], v[56:59]
	v_mfma_f32_16x16x32_bf16 v[52:55], v[144:147], v[210:213], v[52:55]
	v_mfma_f32_16x16x32_bf16 v[48:51], v[178:181], v[210:213], v[48:51]
	v_mfma_f32_16x16x32_bf16 v[36:39], v[144:147], v[224:227], v[36:39]
	v_mfma_f32_16x16x32_bf16 v[32:35], v[178:181], v[224:227], v[32:35]
	v_mfma_f32_16x16x32_bf16 v[20:23], v[144:147], v[232:235], v[20:23]
	v_mfma_f32_16x16x32_bf16 v[16:19], v[178:181], v[232:235], v[16:19]
	s_setprio 0
	s_setprio 1
	v_mfma_f32_16x16x32_bf16 v[44:47], v[182:185], v[198:201], v[44:47]
	v_mfma_f32_16x16x32_bf16 v[40:43], v[190:193], v[198:201], v[40:43]
	v_mfma_f32_16x16x32_bf16 v[28:31], v[182:185], v[206:209], v[28:31]
	v_mfma_f32_16x16x32_bf16 v[24:27], v[190:193], v[206:209], v[24:27]
	v_mfma_f32_16x16x32_bf16 v[12:15], v[182:185], v[220:223], v[12:15]
	v_mfma_f32_16x16x32_bf16 v[8:11], v[190:193], v[220:223], v[8:11]
	v_mfma_f32_16x16x32_bf16 v[4:7], v[182:185], v[228:231], v[4:7]
	v_mfma_f32_16x16x32_bf16 v[0:3], v[190:193], v[228:231], v[0:3]
	v_mfma_f32_16x16x32_bf16 v[44:47], v[186:189], v[202:205], v[44:47]
	v_mfma_f32_16x16x32_bf16 v[40:43], v[194:197], v[202:205], v[40:43]
	v_mfma_f32_16x16x32_bf16 v[28:31], v[186:189], v[210:213], v[28:31]
	v_mfma_f32_16x16x32_bf16 v[24:27], v[194:197], v[210:213], v[24:27]
	v_mfma_f32_16x16x32_bf16 v[12:15], v[186:189], v[224:227], v[12:15]
	v_mfma_f32_16x16x32_bf16 v[8:11], v[194:197], v[224:227], v[8:11]
	v_mfma_f32_16x16x32_bf16 v[4:7], v[186:189], v[232:235], v[4:7]
	v_mfma_f32_16x16x32_bf16 v[0:3], v[194:197], v[232:235], v[0:3]
	s_setprio 0
	s_barrier
	s_add_i32 s57, 0, 0x18000
	v_add_u32_e32 v152, s57, v151
	s_add_i32 s58, 0, 0x1c000
	ds_read_b128 v[140:143], v152
	ds_read_b128 v[144:147], v152 offset:1024
	ds_read_b128 v[174:177], v152 offset:2048
	ds_read_b128 v[178:181], v152 offset:3072
	v_add_u32_e32 v152, s58, v151
	ds_read_b128 v[182:185], v152
	ds_read_b128 v[186:189], v152 offset:1024
	ds_read_b128 v[190:193], v152 offset:2048
	ds_read_b128 v[194:197], v152 offset:3072
	s_add_u32 s48, s48, 0x80000
	s_addc_u32 s49, s49, 0
	s_mov_b32 m0, s33
	v_lshl_add_u64 v[240:241], s[48:49], 0, v[134:135]
	ds_read_b128 v[198:201], v172 offset:32768
	ds_read_b128 v[202:205], v172 offset:33792
	ds_read_b128 v[206:209], v172 offset:34816
	ds_read_b128 v[210:213], v172 offset:35840
	ds_read_b128 v[220:223], v172 offset:36864
	ds_read_b128 v[224:227], v172 offset:37888
	ds_read_b128 v[228:231], v172 offset:38912
	ds_read_b128 v[232:235], v172 offset:39936
	global_load_lds_dwordx4 v[240:241], off
	v_lshl_add_u64 v[240:241], s[48:49], 0, v[130:131]
	s_mov_b32 m0, s50
	s_nop 0
	global_load_lds_dwordx4 v[240:241], off
	s_waitcnt vmcnt(8)
	s_waitcnt lgkmcnt(0)
	s_setprio 1
	s_barrier
	s_waitcnt lgkmcnt(0)
	v_mfma_f32_16x16x32_bf16 v[124:127], v[140:143], v[198:201], v[124:127]
	v_mfma_f32_16x16x32_bf16 v[120:123], v[174:177], v[198:201], v[120:123]
	v_mfma_f32_16x16x32_bf16 v[116:119], v[140:143], v[206:209], v[116:119]
	v_mfma_f32_16x16x32_bf16 v[112:115], v[174:177], v[206:209], v[112:115]
	v_mfma_f32_16x16x32_bf16 v[100:103], v[140:143], v[220:223], v[100:103]
	v_mfma_f32_16x16x32_bf16 v[96:99], v[174:177], v[220:223], v[96:99]
	v_mfma_f32_16x16x32_bf16 v[84:87], v[140:143], v[228:231], v[84:87]
	v_mfma_f32_16x16x32_bf16 v[80:83], v[174:177], v[228:231], v[80:83]
	v_mfma_f32_16x16x32_bf16 v[124:127], v[144:147], v[202:205], v[124:127]
	v_mfma_f32_16x16x32_bf16 v[120:123], v[178:181], v[202:205], v[120:123]
	v_mfma_f32_16x16x32_bf16 v[116:119], v[144:147], v[210:213], v[116:119]
	v_mfma_f32_16x16x32_bf16 v[112:115], v[178:181], v[210:213], v[112:115]
	v_mfma_f32_16x16x32_bf16 v[100:103], v[144:147], v[224:227], v[100:103]
	v_mfma_f32_16x16x32_bf16 v[96:99], v[178:181], v[224:227], v[96:99]
	v_mfma_f32_16x16x32_bf16 v[84:87], v[144:147], v[232:235], v[84:87]
	v_mfma_f32_16x16x32_bf16 v[80:83], v[178:181], v[232:235], v[80:83]
	s_setprio 0
	s_setprio 1
	v_mfma_f32_16x16x32_bf16 v[108:111], v[182:185], v[198:201], v[108:111]
	v_mfma_f32_16x16x32_bf16 v[104:107], v[190:193], v[198:201], v[104:107]
	v_mfma_f32_16x16x32_bf16 v[92:95], v[182:185], v[206:209], v[92:95]
	v_mfma_f32_16x16x32_bf16 v[88:91], v[190:193], v[206:209], v[88:91]
	v_mfma_f32_16x16x32_bf16 v[76:79], v[182:185], v[220:223], v[76:79]
	v_mfma_f32_16x16x32_bf16 v[72:75], v[190:193], v[220:223], v[72:75]
	v_mfma_f32_16x16x32_bf16 v[68:71], v[182:185], v[228:231], v[68:71]
	v_mfma_f32_16x16x32_bf16 v[64:67], v[190:193], v[228:231], v[64:67]
	v_mfma_f32_16x16x32_bf16 v[108:111], v[186:189], v[202:205], v[108:111]
	v_mfma_f32_16x16x32_bf16 v[104:107], v[194:197], v[202:205], v[104:107]
	v_mfma_f32_16x16x32_bf16 v[92:95], v[186:189], v[210:213], v[92:95]
	v_mfma_f32_16x16x32_bf16 v[88:91], v[194:197], v[210:213], v[88:91]
	v_mfma_f32_16x16x32_bf16 v[76:79], v[186:189], v[224:227], v[76:79]
	v_mfma_f32_16x16x32_bf16 v[72:75], v[194:197], v[224:227], v[72:75]
	v_mfma_f32_16x16x32_bf16 v[68:71], v[186:189], v[232:235], v[68:71]
	v_mfma_f32_16x16x32_bf16 v[64:67], v[194:197], v[232:235], v[64:67]
	s_setprio 0
	s_barrier
; #define PG8_STAGE(bufoff, gbase, voff) do { _Pragma("unroll") for (int _i = 0; _i < 2; ++_i) \
;         __builtin_amdgcn_global_load_lds((const unsigned*)((const char*)(gbase) + (voff)[_i]), (PG8_LAS unsigned*)(lds + (bufoff) + ldsw + _i * 8192), 16, 0, 0); } while (0)
; #define PG8_LDA(dst, b, h) do { _Pragma("unroll") for (int m = 0; m < 4; ++m) _Pragma("unroll") for (int k = 0; k < 2; ++k) dst[m][k] = *(const PG8_LAS bf16x8*)(lds + PG8_SA(b, h) + aoff + m * 2048 + k * 1024); } while (0)
; #define PG8_MMA(ai, bj, At, Bt) do { __builtin_amdgcn_s_setprio(1); _Pragma("unroll") for (int m = 0; m < 4; ++m) _Pragma("unroll") for (int n = 0; n < 2; ++n) _Pragma("unroll") for (int k = 0; k < 2; ++k) \
;         acc[ai][bj][m][n] = __builtin_amdgcn_mfma_f32_16x16x32_bf16(Bt[n][k], At[m][k], acc[ai][bj][m][n], 0, 0, 0); __builtin_amdgcn_s_setprio(0); } while (0)
; #define PG8_WAIT_V(n) asm volatile("s_waitcnt vmcnt(" #n ")" ::: "memory")
; #define PG8_WAIT_L(n) asm volatile("s_waitcnt lgkmcnt(" #n ")" ::: "memory")
; #define PG8_BAR __builtin_amdgcn_s_barrier()
; #define PG8_SCHED __builtin_amdgcn_sched_barrier(0)
; template <class Epi, class Sched, bool ALIGN_EPI = false, bool SP2 = false>
; __device__ __forceinline__ void gemm_phase(PG8_LAS unsigned char* lds, const Gemm g, const Sched& S, const Epi& E) {
;     ...
;         for (int t = 0; t < nt; t += 2) {
;             const bool last = (t == nt - 2);
;             const char* a1 = cA + (size_t)(t + 1) * kstep;
;             const char* a2 = last ? nA : cA + (size_t)(t + 2) * kstep; const char* b2 = last ? nB : cB + (size_t)(t + 2) * kstep;
;     ...
;             PG8_WAIT_V(8); PG8_WAIT_L(0); PG8_BAR; PG8_MMA(0, 0, At, B0); PG8_MMA(0, 1, At, B1); PG8_BAR; PG8_SCHED;
;             PG8_LDA(At, 1, 1); PG8_STAGE(PG8_SB(1, 0), b3, voffB); PG8_STAGE(PG8_SB(1, 1), b3 + hstep, voffB); PG8_STAGE(PG8_SA(1, 0), a3, voffA);
;             PG8_WAIT_V(8); PG8_WAIT_L(0); PG8_BAR; PG8_MMA(1, 0, At, B0); PG8_MMA(1, 1, At, B1); PG8_BAR; PG8_SCHED;
	s_add_i32 s48, s57, s26
	v_lshl_add_u64 v[148:149], v[148:149], 0, s[90:91]
	s_mov_b32 m0, s48
	ds_read_b128 v[198:201], v172 offset:49152
	ds_read_b128 v[202:205], v172 offset:50176
	ds_read_b128 v[206:209], v172 offset:51200
	ds_read_b128 v[210:213], v172 offset:52224
	ds_read_b128 v[220:223], v172 offset:53248
	ds_read_b128 v[224:227], v172 offset:54272
	ds_read_b128 v[228:231], v172 offset:55296
	ds_read_b128 v[232:235], v172 offset:56320
	global_load_lds_dwordx4 v[148:149], off
	s_add_i32 m0, s48, 0x2000
	s_add_u32 s46, s46, 0x80080
	v_lshl_add_u64 v[148:149], v[214:215], 0, s[90:91]
	s_addc_u32 s47, s47, 0
	s_add_i32 s48, s58, s26
	global_load_lds_dwordx4 v[148:149], off
	v_lshl_add_u64 v[148:149], s[46:47], 0, v[132:133]
	s_mov_b32 m0, s48
	s_nop 0
	global_load_lds_dwordx4 v[148:149], off
	v_lshl_add_u64 v[148:149], s[46:47], 0, v[128:129]
	s_add_i32 m0, s48, 0x2000
	s_nop 0
	global_load_lds_dwordx4 v[148:149], off
	v_lshl_add_u64 v[148:149], v[236:237], 0, s[90:91]
	s_mov_b32 m0, s4
	s_nop 0
	global_load_lds_dwordx4 v[148:149], off
	v_lshl_add_u64 v[148:149], v[238:239], 0, s[90:91]
	s_mov_b32 m0, s51
	s_nop 0
	global_load_lds_dwordx4 v[148:149], off
	s_waitcnt vmcnt(8)
	s_waitcnt lgkmcnt(0)
	s_setprio 1
	s_barrier
	s_waitcnt lgkmcnt(0)
	v_mfma_f32_16x16x32_bf16 v[60:63], v[140:143], v[198:201], v[60:63]
	v_mfma_f32_16x16x32_bf16 v[56:59], v[174:177], v[198:201], v[56:59]
	v_mfma_f32_16x16x32_bf16 v[52:55], v[140:143], v[206:209], v[52:55]
	v_mfma_f32_16x16x32_bf16 v[48:51], v[174:177], v[206:209], v[48:51]
	v_mfma_f32_16x16x32_bf16 v[36:39], v[140:143], v[220:223], v[36:39]
	v_mfma_f32_16x16x32_bf16 v[32:35], v[174:177], v[220:223], v[32:35]
	v_mfma_f32_16x16x32_bf16 v[20:23], v[140:143], v[228:231], v[20:23]
	v_mfma_f32_16x16x32_bf16 v[16:19], v[174:177], v[228:231], v[16:19]
	v_mfma_f32_16x16x32_bf16 v[60:63], v[144:147], v[202:205], v[60:63]
	v_mfma_f32_16x16x32_bf16 v[56:59], v[178:181], v[202:205], v[56:59]
	v_mfma_f32_16x16x32_bf16 v[52:55], v[144:147], v[210:213], v[52:55]
	v_mfma_f32_16x16x32_bf16 v[48:51], v[178:181], v[210:213], v[48:51]
	v_mfma_f32_16x16x32_bf16 v[36:39], v[144:147], v[224:227], v[36:39]
	v_mfma_f32_16x16x32_bf16 v[32:35], v[178:181], v[224:227], v[32:35]
	v_mfma_f32_16x16x32_bf16 v[20:23], v[144:147], v[232:235], v[20:23]
	v_mfma_f32_16x16x32_bf16 v[16:19], v[178:181], v[232:235], v[16:19]
	s_setprio 0
	s_setprio 1
	v_mfma_f32_16x16x32_bf16 v[44:47], v[182:185], v[198:201], v[44:47]
	v_mfma_f32_16x16x32_bf16 v[40:43], v[190:193], v[198:201], v[40:43]
	v_mfma_f32_16x16x32_bf16 v[28:31], v[182:185], v[206:209], v[28:31]
	v_mfma_f32_16x16x32_bf16 v[24:27], v[190:193], v[206:209], v[24:27]
	v_mfma_f32_16x16x32_bf16 v[12:15], v[182:185], v[220:223], v[12:15]
	v_mfma_f32_16x16x32_bf16 v[8:11], v[190:193], v[220:223], v[8:11]
	v_mfma_f32_16x16x32_bf16 v[4:7], v[182:185], v[228:231], v[4:7]
	v_mfma_f32_16x16x32_bf16 v[0:3], v[190:193], v[228:231], v[0:3]
	v_mfma_f32_16x16x32_bf16 v[44:47], v[186:189], v[202:205], v[44:47]
	v_mfma_f32_16x16x32_bf16 v[40:43], v[194:197], v[202:205], v[40:43]
	v_mfma_f32_16x16x32_bf16 v[28:31], v[186:189], v[210:213], v[28:31]
	v_mfma_f32_16x16x32_bf16 v[24:27], v[194:197], v[210:213], v[24:27]
	v_mfma_f32_16x16x32_bf16 v[12:15], v[186:189], v[224:227], v[12:15]
	v_mfma_f32_16x16x32_bf16 v[8:11], v[194:197], v[224:227], v[8:11]
	v_mfma_f32_16x16x32_bf16 v[4:7], v[186:189], v[232:235], v[4:7]
	v_mfma_f32_16x16x32_bf16 v[0:3], v[194:197], v[232:235], v[0:3]
	s_setprio 0
	s_barrier
	s_add_i32 s56, s56, 2
	s_add_u32 s44, s44, 0x100
	s_addc_u32 s45, s45, 0
	s_add_u32 s54, s54, 0x100
	s_addc_u32 s55, s55, 0
	s_cmp_gt_u32 s56, 29
	s_cbranch_scc0 .LBB0_57
	s_and_b64 vcc, exec, s[12:13]
	s_cbranch_vccz .LBB0_60
	s_barrier

; #define PG8_STAGE(bufoff, gbase, voff) do { _Pragma("unroll") for (int _i = 0; _i < 2; ++_i) \
;         __builtin_amdgcn_global_load_lds((const unsigned*)((const char*)(gbase) + (voff)[_i]), (PG8_LAS unsigned*)(lds + (bufoff) + ldsw + _i * 8192), 16, 0, 0); } while (0)
; #define PG8_LDA(dst, b, h) do { _Pragma("unroll") for (int m = 0; m < 4; ++m) _Pragma("unroll") for (int k = 0; k < 2; ++k) dst[m][k] = *(const PG8_LAS bf16x8*)(lds + PG8_SA(b, h) + aoff + m * 2048 + k * 1024); } while (0)
; #define PG8_LDB(dst, b, h) do { _Pragma("unroll") for (int n = 0; n < 2; ++n) _Pragma("unroll") for (int k = 0; k < 2; ++k) dst[n][k] = *(const PG8_LAS bf16x8*)(lds + PG8_SB(b, h) + boff + n * 2048 + k * 1024); } while (0)
; #define PG8_MMA(ai, bj, At, Bt) do { __builtin_amdgcn_s_setprio(1); _Pragma("unroll") for (int m = 0; m < 4; ++m) _Pragma("unroll") for (int n = 0; n < 2; ++n) _Pragma("unroll") for (int k = 0; k < 2; ++k) \
;         acc[ai][bj][m][n] = __builtin_amdgcn_mfma_f32_16x16x32_bf16(Bt[n][k], At[m][k], acc[ai][bj][m][n], 0, 0, 0); __builtin_amdgcn_s_setprio(0); } while (0)
; #define PG8_WAIT_V(n) asm volatile("s_waitcnt vmcnt(" #n ")" ::: "memory")
; #define PG8_WAIT_L(n) asm volatile("s_waitcnt lgkmcnt(" #n ")" ::: "memory")
; template <class Epi, class Sched, bool ALIGN_EPI = false, bool SP2 = false>
; __device__ __forceinline__ void gemm_phase(PG8_LAS unsigned char* lds, const Gemm g, const Sched& S, const Epi& E) {
;     ...
;             const bool last = (t == nt - 2);
;             const char* a1 = cA + (size_t)(t + 1) * kstep;
;             const char* a2 = last ? nA : cA + (size_t)(t + 2) * kstep; const char* b2 = last ? nB : cB + (size_t)(t + 2) * kstep;
;             const char* a3 = a2 + kstep; const char* b3 = b2 + kstep;
;             if (last && has_next) S.a_ready(nxt);
;             if constexpr (SP2) {
;             PG8_LDB(B0, 0, 0); PG8_LDB(B1, 0, 1); PG8_SCHED; PG8_LDA(At, 0, 0); PG8_STAGE(PG8_SA(1, 1), a1 + hstep, voffA);
;             PG8_WAIT_V(8); PG8_WAIT_L(0); PG8_BAR; PG8_MMA(0, 0, At, B0); PG8_MMA(0, 1, At, B1); PG8_BAR; PG8_SCHED;
;             PG8_LDA(At, 0, 1); PG8_STAGE(PG8_SB(0, 0), b2, voffB); PG8_STAGE(PG8_SB(0, 1), b2 + hstep, voffB); PG8_STAGE(PG8_SA(0, 0), a2, voffA);
;             PG8_WAIT_V(8); PG8_WAIT_L(0); PG8_BAR; PG8_MMA(1, 0, At, B0); PG8_MMA(1, 1, At, B1); PG8_BAR; PG8_SCHED;
.LBB0_231:
	s_add_u32 s33, s42, 0xfff80080
	s_addc_u32 s44, s43, -1
	s_add_i32 s57, 0, 0x10000
	s_cmp_eq_u32 s29, 28
	s_cselect_b32 s47, s13, s44
	s_cselect_b32 s46, s25, s33
	s_cselect_b32 s45, s11, s28
	s_cselect_b32 s44, s26, s27
	s_add_i32 s33, 0, 0x14000
	v_add_u32_e32 v140, s57, v192
	v_add_u32_e32 v188, s33, v192
	ds_read_b128 v[128:131], v140
	ds_read_b128 v[132:135], v140 offset:1024
	ds_read_b128 v[136:139], v140 offset:2048
	ds_read_b128 v[140:143], v140 offset:3072
	ds_read_b128 v[176:179], v188
	ds_read_b128 v[180:183], v188 offset:1024
	ds_read_b128 v[184:187], v188 offset:2048
	ds_read_b128 v[198:201], v188 offset:3072
	v_lshl_add_u64 v[188:189], s[42:43], 0, v[172:173]
	s_add_i32 m0, s50, 0xc000
	ds_read_b128 v[202:205], v197
	ds_read_b128 v[206:209], v197 offset:1024
	ds_read_b128 v[210:213], v197 offset:2048
	ds_read_b128 v[220:223], v197 offset:3072
	ds_read_b128 v[224:227], v197 offset:4096
	ds_read_b128 v[228:231], v197 offset:5120
	ds_read_b128 v[232:235], v197 offset:6144
	ds_read_b128 v[236:239], v197 offset:7168
	global_load_lds_dwordx4 v[188:189], off
	v_lshl_add_u64 v[188:189], s[42:43], 0, v[174:175]
	s_add_i32 m0, s50, 0xe000
	s_nop 0
	global_load_lds_dwordx4 v[188:189], off
	s_waitcnt vmcnt(8)
	s_waitcnt lgkmcnt(0)
	s_setprio 1
	s_barrier
	s_waitcnt lgkmcnt(0)
	v_mfma_f32_16x16x32_bf16 v[124:127], v[128:131], v[202:205], v[124:127]
	v_mfma_f32_16x16x32_bf16 v[120:123], v[136:139], v[202:205], v[120:123]
	v_mfma_f32_16x16x32_bf16 v[116:119], v[128:131], v[210:213], v[116:119]
	v_mfma_f32_16x16x32_bf16 v[112:115], v[136:139], v[210:213], v[112:115]
	v_mfma_f32_16x16x32_bf16 v[100:103], v[128:131], v[224:227], v[100:103]
	v_mfma_f32_16x16x32_bf16 v[96:99], v[136:139], v[224:227], v[96:99]
	v_mfma_f32_16x16x32_bf16 v[84:87], v[128:131], v[232:235], v[84:87]
	v_mfma_f32_16x16x32_bf16 v[80:83], v[136:139], v[232:235], v[80:83]
	v_mfma_f32_16x16x32_bf16 v[124:127], v[132:135], v[206:209], v[124:127]
	v_mfma_f32_16x16x32_bf16 v[120:123], v[140:143], v[206:209], v[120:123]
	v_mfma_f32_16x16x32_bf16 v[116:119], v[132:135], v[220:223], v[116:119]
	v_mfma_f32_16x16x32_bf16 v[112:115], v[140:143], v[220:223], v[112:115]
	v_mfma_f32_16x16x32_bf16 v[100:103], v[132:135], v[228:231], v[100:103]
	v_mfma_f32_16x16x32_bf16 v[96:99], v[140:143], v[228:231], v[96:99]
	v_mfma_f32_16x16x32_bf16 v[84:87], v[132:135], v[236:239], v[84:87]
	v_mfma_f32_16x16x32_bf16 v[80:83], v[140:143], v[236:239], v[80:83]
	s_setprio 0
	s_setprio 1
	v_mfma_f32_16x16x32_bf16 v[108:111], v[176:179], v[202:205], v[108:111]
	v_mfma_f32_16x16x32_bf16 v[104:107], v[184:187], v[202:205], v[104:107]
	v_mfma_f32_16x16x32_bf16 v[92:95], v[176:179], v[210:213], v[92:95]
	v_mfma_f32_16x16x32_bf16 v[88:91], v[184:187], v[210:213], v[88:91]
	v_mfma_f32_16x16x32_bf16 v[76:79], v[176:179], v[224:227], v[76:79]
	v_mfma_f32_16x16x32_bf16 v[72:75], v[184:187], v[224:227], v[72:75]
	v_mfma_f32_16x16x32_bf16 v[68:71], v[176:179], v[232:235], v[68:71]
	v_mfma_f32_16x16x32_bf16 v[64:67], v[184:187], v[232:235], v[64:67]
	v_mfma_f32_16x16x32_bf16 v[108:111], v[180:183], v[206:209], v[108:111]
	v_mfma_f32_16x16x32_bf16 v[104:107], v[198:201], v[206:209], v[104:107]
	v_mfma_f32_16x16x32_bf16 v[92:95], v[180:183], v[220:223], v[92:95]
	v_mfma_f32_16x16x32_bf16 v[88:91], v[198:201], v[220:223], v[88:91]
	v_mfma_f32_16x16x32_bf16 v[76:79], v[180:183], v[228:231], v[76:79]
	v_mfma_f32_16x16x32_bf16 v[72:75], v[198:201], v[228:231], v[72:75]
	v_mfma_f32_16x16x32_bf16 v[68:71], v[180:183], v[236:239], v[68:71]
	v_mfma_f32_16x16x32_bf16 v[64:67], v[198:201], v[236:239], v[64:67]
	s_setprio 0
	s_barrier
	s_add_i32 s57, s57, s48
	v_lshl_add_u64 v[188:189], s[44:45], 0, v[152:153]
	s_mov_b32 m0, s57
	ds_read_b128 v[202:205], v197 offset:16384
	ds_read_b128 v[206:209], v197 offset:17408
	ds_read_b128 v[210:213], v197 offset:18432
	ds_read_b128 v[220:223], v197 offset:19456
	ds_read_b128 v[224:227], v197 offset:20480
	ds_read_b128 v[228:231], v197 offset:21504
	ds_read_b128 v[232:235], v197 offset:22528
	ds_read_b128 v[236:239], v197 offset:23552
	global_load_lds_dwordx4 v[188:189], off
	s_add_i32 m0, s57, 0x2000
	s_add_u32 s58, s44, 0x80000
	v_lshl_add_u64 v[214:215], s[44:45], 0, v[144:145]
	s_addc_u32 s59, s45, 0
	s_add_i32 s33, s33, s48
	global_load_lds_dwordx4 v[214:215], off
	v_lshl_add_u64 v[240:241], s[58:59], 0, v[152:153]
	s_mov_b32 m0, s33
	v_lshl_add_u64 v[242:243], s[46:47], 0, v[146:147]
	global_load_lds_dwordx4 v[240:241], off
	v_lshl_add_u64 v[240:241], s[58:59], 0, v[144:145]
	s_add_i32 m0, s33, 0x2000
	s_nop 0
	global_load_lds_dwordx4 v[240:241], off
	v_lshl_add_u64 v[240:241], s[46:47], 0, v[148:149]
	s_mov_b32 m0, s50
	s_nop 0
	global_load_lds_dwordx4 v[240:241], off
	s_mov_b32 m0, s51
	s_nop 0
	global_load_lds_dwordx4 v[242:243], off
	s_waitcnt vmcnt(8)
	s_waitcnt lgkmcnt(0)
	s_setprio 1
	s_barrier
; #define PG8_STAGE(bufoff, gbase, voff) do { _Pragma("unroll") for (int _i = 0; _i < 2; ++_i) \
;         __builtin_amdgcn_global_load_lds((const unsigned*)((const char*)(gbase) + (voff)[_i]), (PG8_LAS unsigned*)(lds + (bufoff) + ldsw + _i * 8192), 16, 0, 0); } while (0)
; #define PG8_LDA(dst, b, h) do { _Pragma("unroll") for (int m = 0; m < 4; ++m) _Pragma("unroll") for (int k = 0; k < 2; ++k) dst[m][k] = *(const PG8_LAS bf16x8*)(lds + PG8_SA(b, h) + aoff + m * 2048 + k * 1024); } while (0)
; #define PG8_LDB(dst, b, h) do { _Pragma("unroll") for (int n = 0; n < 2; ++n) _Pragma("unroll") for (int k = 0; k < 2; ++k) dst[n][k] = *(const PG8_LAS bf16x8*)(lds + PG8_SB(b, h) + boff + n * 2048 + k * 1024); } while (0)
; #define PG8_MMA(ai, bj, At, Bt) do { __builtin_amdgcn_s_setprio(1); _Pragma("unroll") for (int m = 0; m < 4; ++m) _Pragma("unroll") for (int n = 0; n < 2; ++n) _Pragma("unroll") for (int k = 0; k < 2; ++k) \
;         acc[ai][bj][m][n] = __builtin_amdgcn_mfma_f32_16x16x32_bf16(Bt[n][k], At[m][k], acc[ai][bj][m][n], 0, 0, 0); __builtin_amdgcn_s_setprio(0); } while (0)
; #define PG8_WAIT_V(n) asm volatile("s_waitcnt vmcnt(" #n ")" ::: "memory")
; #define PG8_WAIT_L(n) asm volatile("s_waitcnt lgkmcnt(" #n ")" ::: "memory")
; #define PG8_BAR __builtin_amdgcn_s_barrier()
; #define PG8_SCHED __builtin_amdgcn_sched_barrier(0)
; template <class Epi, class Sched, bool ALIGN_EPI = false, bool SP2 = false>
; __device__ __forceinline__ void gemm_phase(PG8_LAS unsigned char* lds, const Gemm g, const Sched& S, const Epi& E) {
;     ...
;             PG8_WAIT_V(8); PG8_WAIT_L(0); PG8_BAR; PG8_MMA(1, 0, At, B0); PG8_MMA(1, 1, At, B1); PG8_BAR; PG8_SCHED;
;             PG8_LDB(B0, 1, 0); PG8_LDB(B1, 1, 1); PG8_SCHED; PG8_LDA(At, 1, 0); PG8_STAGE(PG8_SA(0, 1), a2 + hstep, voffA);
;             PG8_WAIT_V(8); PG8_WAIT_L(0); PG8_BAR; PG8_MMA(0, 0, At, B0); PG8_MMA(0, 1, At, B1); PG8_BAR; PG8_SCHED;
	s_waitcnt lgkmcnt(0)
	v_mfma_f32_16x16x32_bf16 v[60:63], v[128:131], v[202:205], v[60:63]
	v_mfma_f32_16x16x32_bf16 v[56:59], v[136:139], v[202:205], v[56:59]
	v_mfma_f32_16x16x32_bf16 v[52:55], v[128:131], v[210:213], v[52:55]
	v_mfma_f32_16x16x32_bf16 v[48:51], v[136:139], v[210:213], v[48:51]
	v_mfma_f32_16x16x32_bf16 v[36:39], v[128:131], v[224:227], v[36:39]
	v_mfma_f32_16x16x32_bf16 v[32:35], v[136:139], v[224:227], v[32:35]
	v_mfma_f32_16x16x32_bf16 v[20:23], v[128:131], v[232:235], v[20:23]
	v_mfma_f32_16x16x32_bf16 v[16:19], v[136:139], v[232:235], v[16:19]
	v_mfma_f32_16x16x32_bf16 v[60:63], v[132:135], v[206:209], v[60:63]
	v_mfma_f32_16x16x32_bf16 v[56:59], v[140:143], v[206:209], v[56:59]
	v_mfma_f32_16x16x32_bf16 v[52:55], v[132:135], v[220:223], v[52:55]
	v_mfma_f32_16x16x32_bf16 v[48:51], v[140:143], v[220:223], v[48:51]
	v_mfma_f32_16x16x32_bf16 v[36:39], v[132:135], v[228:231], v[36:39]
	v_mfma_f32_16x16x32_bf16 v[32:35], v[140:143], v[228:231], v[32:35]
	v_mfma_f32_16x16x32_bf16 v[20:23], v[132:135], v[236:239], v[20:23]
	v_mfma_f32_16x16x32_bf16 v[16:19], v[140:143], v[236:239], v[16:19]
	s_setprio 0
	s_setprio 1
	v_mfma_f32_16x16x32_bf16 v[44:47], v[176:179], v[202:205], v[44:47]
	v_mfma_f32_16x16x32_bf16 v[40:43], v[184:187], v[202:205], v[40:43]
	v_mfma_f32_16x16x32_bf16 v[28:31], v[176:179], v[210:213], v[28:31]
	v_mfma_f32_16x16x32_bf16 v[24:27], v[184:187], v[210:213], v[24:27]
	v_mfma_f32_16x16x32_bf16 v[12:15], v[176:179], v[224:227], v[12:15]
	v_mfma_f32_16x16x32_bf16 v[8:11], v[184:187], v[224:227], v[8:11]
	v_mfma_f32_16x16x32_bf16 v[4:7], v[176:179], v[232:235], v[4:7]
	v_mfma_f32_16x16x32_bf16 v[0:3], v[184:187], v[232:235], v[0:3]
	v_mfma_f32_16x16x32_bf16 v[44:47], v[180:183], v[206:209], v[44:47]
	v_mfma_f32_16x16x32_bf16 v[40:43], v[198:201], v[206:209], v[40:43]
	v_mfma_f32_16x16x32_bf16 v[28:31], v[180:183], v[220:223], v[28:31]
	v_mfma_f32_16x16x32_bf16 v[24:27], v[198:201], v[220:223], v[24:27]
	v_mfma_f32_16x16x32_bf16 v[12:15], v[180:183], v[228:231], v[12:15]
	v_mfma_f32_16x16x32_bf16 v[8:11], v[198:201], v[228:231], v[8:11]
	v_mfma_f32_16x16x32_bf16 v[4:7], v[180:183], v[236:239], v[4:7]
	v_mfma_f32_16x16x32_bf16 v[0:3], v[198:201], v[236:239], v[0:3]
	s_setprio 0
	s_barrier
	s_add_i32 s33, 0, 0x18000
	s_add_i32 s57, 0, 0x1c000
	v_add_u32_e32 v140, s33, v192
	v_add_u32_e32 v198, s57, v192
	ds_read_b128 v[128:131], v140
	ds_read_b128 v[132:135], v140 offset:1024
	ds_read_b128 v[136:139], v140 offset:2048
	ds_read_b128 v[140:143], v140 offset:3072
	ds_read_b128 v[176:179], v198
	ds_read_b128 v[180:183], v198 offset:1024
	ds_read_b128 v[184:187], v198 offset:2048
	ds_read_b128 v[198:201], v198 offset:3072
	s_add_u32 s46, s46, 0x80000
	s_addc_u32 s47, s47, 0
	s_mov_b32 m0, s52
	v_lshl_add_u64 v[244:245], s[46:47], 0, v[148:149]
	ds_read_b128 v[202:205], v197 offset:32768
	ds_read_b128 v[206:209], v197 offset:33792
	ds_read_b128 v[210:213], v197 offset:34816
	ds_read_b128 v[220:223], v197 offset:35840
	ds_read_b128 v[224:227], v197 offset:36864
	ds_read_b128 v[228:231], v197 offset:37888
	ds_read_b128 v[232:235], v197 offset:38912
	ds_read_b128 v[236:239], v197 offset:39936
	global_load_lds_dwordx4 v[244:245], off
	v_lshl_add_u64 v[244:245], s[46:47], 0, v[146:147]
	s_mov_b32 m0, s53
	s_nop 0
	global_load_lds_dwordx4 v[244:245], off
	s_waitcnt vmcnt(8)
	s_waitcnt lgkmcnt(0)
	s_setprio 1
	s_barrier
	s_waitcnt lgkmcnt(0)
	v_mfma_f32_16x16x32_bf16 v[124:127], v[128:131], v[202:205], v[124:127]
	v_mfma_f32_16x16x32_bf16 v[120:123], v[136:139], v[202:205], v[120:123]
	v_mfma_f32_16x16x32_bf16 v[116:119], v[128:131], v[210:213], v[116:119]
	v_mfma_f32_16x16x32_bf16 v[112:115], v[136:139], v[210:213], v[112:115]
	v_mfma_f32_16x16x32_bf16 v[100:103], v[128:131], v[224:227], v[100:103]
	v_mfma_f32_16x16x32_bf16 v[96:99], v[136:139], v[224:227], v[96:99]
	v_mfma_f32_16x16x32_bf16 v[84:87], v[128:131], v[232:235], v[84:87]
	v_mfma_f32_16x16x32_bf16 v[80:83], v[136:139], v[232:235], v[80:83]
	v_mfma_f32_16x16x32_bf16 v[124:127], v[132:135], v[206:209], v[124:127]
	v_mfma_f32_16x16x32_bf16 v[120:123], v[140:143], v[206:209], v[120:123]
	v_mfma_f32_16x16x32_bf16 v[116:119], v[132:135], v[220:223], v[116:119]
	v_mfma_f32_16x16x32_bf16 v[112:115], v[140:143], v[220:223], v[112:115]
	v_mfma_f32_16x16x32_bf16 v[100:103], v[132:135], v[228:231], v[100:103]
	v_mfma_f32_16x16x32_bf16 v[96:99], v[140:143], v[228:231], v[96:99]
	v_mfma_f32_16x16x32_bf16 v[84:87], v[132:135], v[236:239], v[84:87]
	v_mfma_f32_16x16x32_bf16 v[80:83], v[140:143], v[236:239], v[80:83]
	s_setprio 0
	s_setprio 1
	v_mfma_f32_16x16x32_bf16 v[108:111], v[176:179], v[202:205], v[108:111]
	v_mfma_f32_16x16x32_bf16 v[104:107], v[184:187], v[202:205], v[104:107]
	v_mfma_f32_16x16x32_bf16 v[92:95], v[176:179], v[210:213], v[92:95]
	v_mfma_f32_16x16x32_bf16 v[88:91], v[184:187], v[210:213], v[88:91]
	v_mfma_f32_16x16x32_bf16 v[76:79], v[176:179], v[224:227], v[76:79]
	v_mfma_f32_16x16x32_bf16 v[72:75], v[184:187], v[224:227], v[72:75]
	v_mfma_f32_16x16x32_bf16 v[68:71], v[176:179], v[232:235], v[68:71]
	v_mfma_f32_16x16x32_bf16 v[64:67], v[184:187], v[232:235], v[64:67]
	v_mfma_f32_16x16x32_bf16 v[108:111], v[180:183], v[206:209], v[108:111]
	v_mfma_f32_16x16x32_bf16 v[104:107], v[198:201], v[206:209], v[104:107]
	v_mfma_f32_16x16x32_bf16 v[92:95], v[180:183], v[220:223], v[92:95]
	v_mfma_f32_16x16x32_bf16 v[88:91], v[198:201], v[220:223], v[88:91]
	v_mfma_f32_16x16x32_bf16 v[76:79], v[180:183], v[228:231], v[76:79]
	v_mfma_f32_16x16x32_bf16 v[72:75], v[198:201], v[228:231], v[72:75]
	v_mfma_f32_16x16x32_bf16 v[68:71], v[180:183], v[236:239], v[68:71]
	v_mfma_f32_16x16x32_bf16 v[64:67], v[198:201], v[236:239], v[64:67]
	s_setprio 0
	s_barrier
; #define PG8_STAGE(bufoff, gbase, voff) do { _Pragma("unroll") for (int _i = 0; _i < 2; ++_i) \
;         __builtin_amdgcn_global_load_lds((const unsigned*)((const char*)(gbase) + (voff)[_i]), (PG8_LAS unsigned*)(lds + (bufoff) + ldsw + _i * 8192), 16, 0, 0); } while (0)
; #define PG8_LDA(dst, b, h) do { _Pragma("unroll") for (int m = 0; m < 4; ++m) _Pragma("unroll") for (int k = 0; k < 2; ++k) dst[m][k] = *(const PG8_LAS bf16x8*)(lds + PG8_SA(b, h) + aoff + m * 2048 + k * 1024); } while (0)
; #define PG8_MMA(ai, bj, At, Bt) do { __builtin_amdgcn_s_setprio(1); _Pragma("unroll") for (int m = 0; m < 4; ++m) _Pragma("unroll") for (int n = 0; n < 2; ++n) _Pragma("unroll") for (int k = 0; k < 2; ++k) \
;         acc[ai][bj][m][n] = __builtin_amdgcn_mfma_f32_16x16x32_bf16(Bt[n][k], At[m][k], acc[ai][bj][m][n], 0, 0, 0); __builtin_amdgcn_s_setprio(0); } while (0)
; #define PG8_WAIT_V(n) asm volatile("s_waitcnt vmcnt(" #n ")" ::: "memory")
; #define PG8_WAIT_L(n) asm volatile("s_waitcnt lgkmcnt(" #n ")" ::: "memory")
; #define PG8_BAR __builtin_amdgcn_s_barrier()
; #define PG8_SCHED __builtin_amdgcn_sched_barrier(0)
; template <class Epi, class Sched, bool ALIGN_EPI = false, bool SP2 = false>
; __device__ __forceinline__ void gemm_phase(PG8_LAS unsigned char* lds, const Gemm g, const Sched& S, const Epi& E) {
;     ...
;         for (int t = 0; t < nt; t += 2) {
;             const bool last = (t == nt - 2);
;             const char* a1 = cA + (size_t)(t + 1) * kstep;
;             const char* a2 = last ? nA : cA + (size_t)(t + 2) * kstep; const char* b2 = last ? nB : cB + (size_t)(t + 2) * kstep;
;     ...
;             PG8_WAIT_V(8); PG8_WAIT_L(0); PG8_BAR; PG8_MMA(0, 0, At, B0); PG8_MMA(0, 1, At, B1); PG8_BAR; PG8_SCHED;
;             PG8_LDA(At, 1, 1); PG8_STAGE(PG8_SB(1, 0), b3, voffB); PG8_STAGE(PG8_SB(1, 1), b3 + hstep, voffB); PG8_STAGE(PG8_SA(1, 0), a3, voffA);
;             PG8_WAIT_V(8); PG8_WAIT_L(0); PG8_BAR; PG8_MMA(1, 0, At, B0); PG8_MMA(1, 1, At, B1); PG8_BAR; PG8_SCHED;
	s_add_i32 s33, s33, s48
	v_lshl_add_u64 v[188:189], v[188:189], 0, s[90:91]
	s_mov_b32 m0, s33
	ds_read_b128 v[202:205], v197 offset:49152
	ds_read_b128 v[206:209], v197 offset:50176
	ds_read_b128 v[210:213], v197 offset:51200
	ds_read_b128 v[220:223], v197 offset:52224
	ds_read_b128 v[224:227], v197 offset:53248
	ds_read_b128 v[228:231], v197 offset:54272
	ds_read_b128 v[232:235], v197 offset:55296
	ds_read_b128 v[236:239], v197 offset:56320
	global_load_lds_dwordx4 v[188:189], off
	s_add_i32 m0, s33, 0x2000
	s_add_u32 s44, s44, 0x80080
	v_lshl_add_u64 v[188:189], v[214:215], 0, s[90:91]
	s_addc_u32 s45, s45, 0
	s_add_i32 s33, s57, s48
	global_load_lds_dwordx4 v[188:189], off
	v_lshl_add_u64 v[188:189], s[44:45], 0, v[152:153]
	s_mov_b32 m0, s33
	s_nop 0
	global_load_lds_dwordx4 v[188:189], off
	v_lshl_add_u64 v[188:189], s[44:45], 0, v[144:145]
	s_add_i32 m0, s33, 0x2000
	s_nop 0
	global_load_lds_dwordx4 v[188:189], off
	v_lshl_add_u64 v[188:189], v[240:241], 0, s[90:91]
	s_mov_b32 m0, s4
	s_nop 0
	global_load_lds_dwordx4 v[188:189], off
	v_lshl_add_u64 v[188:189], v[242:243], 0, s[90:91]
	s_mov_b32 m0, s54
	s_nop 0
	global_load_lds_dwordx4 v[188:189], off
	s_waitcnt vmcnt(8)
	s_waitcnt lgkmcnt(0)
	s_setprio 1
	s_barrier
	s_waitcnt lgkmcnt(0)
	v_mfma_f32_16x16x32_bf16 v[60:63], v[128:131], v[202:205], v[60:63]
	v_mfma_f32_16x16x32_bf16 v[56:59], v[136:139], v[202:205], v[56:59]
	v_mfma_f32_16x16x32_bf16 v[52:55], v[128:131], v[210:213], v[52:55]
	v_mfma_f32_16x16x32_bf16 v[48:51], v[136:139], v[210:213], v[48:51]
	v_mfma_f32_16x16x32_bf16 v[36:39], v[128:131], v[224:227], v[36:39]
	v_mfma_f32_16x16x32_bf16 v[32:35], v[136:139], v[224:227], v[32:35]
	v_mfma_f32_16x16x32_bf16 v[20:23], v[128:131], v[232:235], v[20:23]
	v_mfma_f32_16x16x32_bf16 v[16:19], v[136:139], v[232:235], v[16:19]
	v_mfma_f32_16x16x32_bf16 v[60:63], v[132:135], v[206:209], v[60:63]
	v_mfma_f32_16x16x32_bf16 v[56:59], v[140:143], v[206:209], v[56:59]
	v_mfma_f32_16x16x32_bf16 v[52:55], v[132:135], v[220:223], v[52:55]
	v_mfma_f32_16x16x32_bf16 v[48:51], v[140:143], v[220:223], v[48:51]
	v_mfma_f32_16x16x32_bf16 v[36:39], v[132:135], v[228:231], v[36:39]
	v_mfma_f32_16x16x32_bf16 v[32:35], v[140:143], v[228:231], v[32:35]
	v_mfma_f32_16x16x32_bf16 v[20:23], v[132:135], v[236:239], v[20:23]
	v_mfma_f32_16x16x32_bf16 v[16:19], v[140:143], v[236:239], v[16:19]
	s_setprio 0
	s_setprio 1
	v_mfma_f32_16x16x32_bf16 v[44:47], v[176:179], v[202:205], v[44:47]
	v_mfma_f32_16x16x32_bf16 v[40:43], v[184:187], v[202:205], v[40:43]
	v_mfma_f32_16x16x32_bf16 v[28:31], v[176:179], v[210:213], v[28:31]
	v_mfma_f32_16x16x32_bf16 v[24:27], v[184:187], v[210:213], v[24:27]
	v_mfma_f32_16x16x32_bf16 v[12:15], v[176:179], v[224:227], v[12:15]
	v_mfma_f32_16x16x32_bf16 v[8:11], v[184:187], v[224:227], v[8:11]
	v_mfma_f32_16x16x32_bf16 v[4:7], v[176:179], v[232:235], v[4:7]
	v_mfma_f32_16x16x32_bf16 v[0:3], v[184:187], v[232:235], v[0:3]
	v_mfma_f32_16x16x32_bf16 v[44:47], v[180:183], v[206:209], v[44:47]
	v_mfma_f32_16x16x32_bf16 v[40:43], v[198:201], v[206:209], v[40:43]
	v_mfma_f32_16x16x32_bf16 v[28:31], v[180:183], v[220:223], v[28:31]
	v_mfma_f32_16x16x32_bf16 v[24:27], v[198:201], v[220:223], v[24:27]
	v_mfma_f32_16x16x32_bf16 v[12:15], v[180:183], v[228:231], v[12:15]
	v_mfma_f32_16x16x32_bf16 v[8:11], v[198:201], v[228:231], v[8:11]
	v_mfma_f32_16x16x32_bf16 v[4:7], v[180:183], v[236:239], v[4:7]
	v_mfma_f32_16x16x32_bf16 v[0:3], v[198:201], v[236:239], v[0:3]
	s_setprio 0
	s_barrier
	s_add_i32 s29, s29, 2
	s_add_u32 s42, s42, 0x100
	s_addc_u32 s43, s43, 0
	s_add_u32 s27, s27, 0x100
	s_addc_u32 s28, s28, 0
	s_cmp_gt_u32 s29, 29
	s_cbranch_scc0 .LBB0_231
	s_and_b64 vcc, exec, s[8:9]
	s_cbranch_vccz .LBB0_234
	s_barrier

; #define PG8_STAGE(bufoff, gbase, voff) do { _Pragma("unroll") for (int _i = 0; _i < 2; ++_i) \
;         __builtin_amdgcn_global_load_lds((const unsigned*)((const char*)(gbase) + (voff)[_i]), (PG8_LAS unsigned*)(lds + (bufoff) + ldsw + _i * 8192), 16, 0, 0); } while (0)
; #define PG8_LDA(dst, b, h) do { _Pragma("unroll") for (int m = 0; m < 4; ++m) _Pragma("unroll") for (int k = 0; k < 2; ++k) dst[m][k] = *(const PG8_LAS bf16x8*)(lds + PG8_SA(b, h) + aoff + m * 2048 + k * 1024); } while (0)
; #define PG8_LDB(dst, b, h) do { _Pragma("unroll") for (int n = 0; n < 2; ++n) _Pragma("unroll") for (int k = 0; k < 2; ++k) dst[n][k] = *(const PG8_LAS bf16x8*)(lds + PG8_SB(b, h) + boff + n * 2048 + k * 1024); } while (0)
; #define PG8_MMA(ai, bj, At, Bt) do { __builtin_amdgcn_s_setprio(1); _Pragma("unroll") for (int m = 0; m < 4; ++m) _Pragma("unroll") for (int n = 0; n < 2; ++n) _Pragma("unroll") for (int k = 0; k < 2; ++k) \
;         acc[ai][bj][m][n] = __builtin_amdgcn_mfma_f32_16x16x32_bf16(Bt[n][k], At[m][k], acc[ai][bj][m][n], 0, 0, 0); __builtin_amdgcn_s_setprio(0); } while (0)
; #define PG8_WAIT_V(n) asm volatile("s_waitcnt vmcnt(" #n ")" ::: "memory")
; #define PG8_WAIT_L(n) asm volatile("s_waitcnt lgkmcnt(" #n ")" ::: "memory")
; template <class Epi, class Sched, bool ALIGN_EPI = false, bool SP2 = false>
; __device__ __forceinline__ void gemm_phase(PG8_LAS unsigned char* lds, const Gemm g, const Sched& S, const Epi& E) {
;     ...
;             const bool last = (t == nt - 2);
;             const char* a1 = cA + (size_t)(t + 1) * kstep;
;             const char* a2 = last ? nA : cA + (size_t)(t + 2) * kstep; const char* b2 = last ? nB : cB + (size_t)(t + 2) * kstep;
;             const char* a3 = a2 + kstep; const char* b3 = b2 + kstep;
;             if (last && has_next) S.a_ready(nxt);
;             if constexpr (SP2) {
;             PG8_LDB(B0, 0, 0); PG8_LDB(B1, 0, 1); PG8_SCHED; PG8_LDA(At, 0, 0); PG8_STAGE(PG8_SA(1, 1), a1 + hstep, voffA);
;             PG8_WAIT_V(8); PG8_WAIT_L(0); PG8_BAR; PG8_MMA(0, 0, At, B0); PG8_MMA(0, 1, At, B1); PG8_BAR; PG8_SCHED;
;             PG8_LDA(At, 0, 1); PG8_STAGE(PG8_SB(0, 0), b2, voffB); PG8_STAGE(PG8_SB(0, 1), b2 + hstep, voffB); PG8_STAGE(PG8_SA(0, 0), a2, voffA);
;             PG8_WAIT_V(8); PG8_WAIT_L(0); PG8_BAR; PG8_MMA(1, 0, At, B0); PG8_MMA(1, 1, At, B1); PG8_BAR; PG8_SCHED;
.LBB0_291:
	s_add_u32 s18, s16, 0x14aba100
	s_addc_u32 s19, s17, 0
	s_add_u32 s44, s16, s41
	s_addc_u32 s45, s17, s42
	s_cmp_eq_u32 s43, 28
	s_cselect_b32 s39, s89, s19
	s_cselect_b32 s38, s88, s18
	s_cselect_b32 s19, s15, s45
	s_cselect_b32 s18, s14, s44
	s_add_i32 s44, 0, 0x10000
	v_add_u32_e32 v150, s44, v140
	s_add_i32 s46, 0, 0x14000
	ds_read_b128 v[142:145], v150
	ds_read_b128 v[146:149], v150 offset:1024
	ds_read_b128 v[170:173], v150 offset:2048
	ds_read_b128 v[174:177], v150 offset:3072
	v_add_u32_e32 v150, s46, v140
	ds_read_b128 v[178:181], v150
	ds_read_b128 v[182:185], v150 offset:1024
	ds_read_b128 v[186:189], v150 offset:2048
	ds_read_b128 v[190:193], v150 offset:3072
	v_lshl_add_u64 v[150:151], s[16:17], 0, v[134:135]
	s_add_i32 m0, s13, 0xc000
	ds_read_b128 v[194:197], v141
	ds_read_b128 v[198:201], v141 offset:1024
	ds_read_b128 v[202:205], v141 offset:2048
	ds_read_b128 v[206:209], v141 offset:3072
	ds_read_b128 v[210:213], v141 offset:4096
	ds_read_b128 v[220:223], v141 offset:5120
	ds_read_b128 v[224:227], v141 offset:6144
	ds_read_b128 v[228:231], v141 offset:7168
	global_load_lds_dwordx4 v[150:151], off
	v_lshl_add_u64 v[150:151], s[16:17], 0, v[136:137]
	s_add_i32 m0, s13, 0xe000
	s_nop 0
	global_load_lds_dwordx4 v[150:151], off
	s_waitcnt vmcnt(8)
	s_waitcnt lgkmcnt(0)
	s_setprio 1
	s_barrier
	s_waitcnt lgkmcnt(0)
	v_mfma_f32_16x16x32_bf16 v[124:127], v[142:145], v[194:197], v[124:127]
	v_mfma_f32_16x16x32_bf16 v[120:123], v[170:173], v[194:197], v[120:123]
	v_mfma_f32_16x16x32_bf16 v[108:111], v[142:145], v[202:205], v[108:111]
	v_mfma_f32_16x16x32_bf16 v[104:107], v[170:173], v[202:205], v[104:107]
	v_mfma_f32_16x16x32_bf16 v[92:95], v[142:145], v[210:213], v[92:95]
	v_mfma_f32_16x16x32_bf16 v[88:91], v[170:173], v[210:213], v[88:91]
	v_mfma_f32_16x16x32_bf16 v[76:79], v[142:145], v[224:227], v[76:79]
	v_mfma_f32_16x16x32_bf16 v[72:75], v[170:173], v[224:227], v[72:75]
	v_mfma_f32_16x16x32_bf16 v[124:127], v[146:149], v[198:201], v[124:127]
	v_mfma_f32_16x16x32_bf16 v[120:123], v[174:177], v[198:201], v[120:123]
	v_mfma_f32_16x16x32_bf16 v[108:111], v[146:149], v[206:209], v[108:111]
	v_mfma_f32_16x16x32_bf16 v[104:107], v[174:177], v[206:209], v[104:107]
	v_mfma_f32_16x16x32_bf16 v[92:95], v[146:149], v[220:223], v[92:95]
	v_mfma_f32_16x16x32_bf16 v[88:91], v[174:177], v[220:223], v[88:91]
	v_mfma_f32_16x16x32_bf16 v[76:79], v[146:149], v[228:231], v[76:79]
	v_mfma_f32_16x16x32_bf16 v[72:75], v[174:177], v[228:231], v[72:75]
	s_setprio 0
	s_setprio 1
	v_mfma_f32_16x16x32_bf16 v[116:119], v[178:181], v[194:197], v[116:119]
	v_mfma_f32_16x16x32_bf16 v[112:115], v[186:189], v[194:197], v[112:115]
	v_mfma_f32_16x16x32_bf16 v[100:103], v[178:181], v[202:205], v[100:103]
	v_mfma_f32_16x16x32_bf16 v[96:99], v[186:189], v[202:205], v[96:99]
	v_mfma_f32_16x16x32_bf16 v[84:87], v[178:181], v[210:213], v[84:87]
	v_mfma_f32_16x16x32_bf16 v[80:83], v[186:189], v[210:213], v[80:83]
	v_mfma_f32_16x16x32_bf16 v[68:71], v[178:181], v[224:227], v[68:71]
	v_mfma_f32_16x16x32_bf16 v[64:67], v[186:189], v[224:227], v[64:67]
	v_mfma_f32_16x16x32_bf16 v[116:119], v[182:185], v[198:201], v[116:119]
	v_mfma_f32_16x16x32_bf16 v[112:115], v[190:193], v[198:201], v[112:115]
	v_mfma_f32_16x16x32_bf16 v[100:103], v[182:185], v[206:209], v[100:103]
	v_mfma_f32_16x16x32_bf16 v[96:99], v[190:193], v[206:209], v[96:99]
	v_mfma_f32_16x16x32_bf16 v[84:87], v[182:185], v[220:223], v[84:87]
	v_mfma_f32_16x16x32_bf16 v[80:83], v[190:193], v[220:223], v[80:83]
	v_mfma_f32_16x16x32_bf16 v[68:71], v[182:185], v[228:231], v[68:71]
	v_mfma_f32_16x16x32_bf16 v[64:67], v[190:193], v[228:231], v[64:67]
	s_setprio 0
	s_barrier
	s_add_i32 s44, s44, s26
	v_lshl_add_u64 v[150:151], s[18:19], 0, v[152:153]
	s_mov_b32 m0, s44
	ds_read_b128 v[194:197], v141 offset:16384
	ds_read_b128 v[198:201], v141 offset:17408
	ds_read_b128 v[202:205], v141 offset:18432
	ds_read_b128 v[206:209], v141 offset:19456
	ds_read_b128 v[210:213], v141 offset:20480
	ds_read_b128 v[220:223], v141 offset:21504
	ds_read_b128 v[224:227], v141 offset:22528
	ds_read_b128 v[228:231], v141 offset:23552
	global_load_lds_dwordx4 v[150:151], off
	s_add_i32 m0, s44, 0x2000
	s_add_u32 s44, s18, 0x80000
	v_lshl_add_u64 v[214:215], s[18:19], 0, v[128:129]
	s_addc_u32 s45, s19, 0
	s_add_i32 s46, s46, s26
	global_load_lds_dwordx4 v[214:215], off
	v_lshl_add_u64 v[232:233], s[44:45], 0, v[152:153]
	s_mov_b32 m0, s46
	v_lshl_add_u64 v[234:235], s[38:39], 0, v[130:131]
	global_load_lds_dwordx4 v[232:233], off
	v_lshl_add_u64 v[232:233], s[44:45], 0, v[128:129]
	s_add_i32 m0, s46, 0x2000
	s_nop 0
	global_load_lds_dwordx4 v[232:233], off
	v_lshl_add_u64 v[232:233], s[38:39], 0, v[132:133]
	s_mov_b32 m0, s13
	s_nop 0
	global_load_lds_dwordx4 v[232:233], off
	s_mov_b32 m0, s27
	s_nop 0
	global_load_lds_dwordx4 v[234:235], off
	s_waitcnt vmcnt(8)
	s_waitcnt lgkmcnt(0)
	s_setprio 1
	s_barrier
; #define PG8_STAGE(bufoff, gbase, voff) do { _Pragma("unroll") for (int _i = 0; _i < 2; ++_i) \
;         __builtin_amdgcn_global_load_lds((const unsigned*)((const char*)(gbase) + (voff)[_i]), (PG8_LAS unsigned*)(lds + (bufoff) + ldsw + _i * 8192), 16, 0, 0); } while (0)
; #define PG8_LDA(dst, b, h) do { _Pragma("unroll") for (int m = 0; m < 4; ++m) _Pragma("unroll") for (int k = 0; k < 2; ++k) dst[m][k] = *(const PG8_LAS bf16x8*)(lds + PG8_SA(b, h) + aoff + m * 2048 + k * 1024); } while (0)
; #define PG8_LDB(dst, b, h) do { _Pragma("unroll") for (int n = 0; n < 2; ++n) _Pragma("unroll") for (int k = 0; k < 2; ++k) dst[n][k] = *(const PG8_LAS bf16x8*)(lds + PG8_SB(b, h) + boff + n * 2048 + k * 1024); } while (0)
; #define PG8_MMA(ai, bj, At, Bt) do { __builtin_amdgcn_s_setprio(1); _Pragma("unroll") for (int m = 0; m < 4; ++m) _Pragma("unroll") for (int n = 0; n < 2; ++n) _Pragma("unroll") for (int k = 0; k < 2; ++k) \
;         acc[ai][bj][m][n] = __builtin_amdgcn_mfma_f32_16x16x32_bf16(Bt[n][k], At[m][k], acc[ai][bj][m][n], 0, 0, 0); __builtin_amdgcn_s_setprio(0); } while (0)
; #define PG8_WAIT_V(n) asm volatile("s_waitcnt vmcnt(" #n ")" ::: "memory")
; #define PG8_WAIT_L(n) asm volatile("s_waitcnt lgkmcnt(" #n ")" ::: "memory")
; #define PG8_BAR __builtin_amdgcn_s_barrier()
; #define PG8_SCHED __builtin_amdgcn_sched_barrier(0)
; template <class Epi, class Sched, bool ALIGN_EPI = false, bool SP2 = false>
; __device__ __forceinline__ void gemm_phase(PG8_LAS unsigned char* lds, const Gemm g, const Sched& S, const Epi& E) {
;     ...
;             PG8_WAIT_V(8); PG8_WAIT_L(0); PG8_BAR; PG8_MMA(1, 0, At, B0); PG8_MMA(1, 1, At, B1); PG8_BAR; PG8_SCHED;
;             PG8_LDB(B0, 1, 0); PG8_LDB(B1, 1, 1); PG8_SCHED; PG8_LDA(At, 1, 0); PG8_STAGE(PG8_SA(0, 1), a2 + hstep, voffA);
;             PG8_WAIT_V(8); PG8_WAIT_L(0); PG8_BAR; PG8_MMA(0, 0, At, B0); PG8_MMA(0, 1, At, B1); PG8_BAR; PG8_SCHED;
	s_waitcnt lgkmcnt(0)
	v_mfma_f32_16x16x32_bf16 v[60:63], v[142:145], v[194:197], v[60:63]
	v_mfma_f32_16x16x32_bf16 v[56:59], v[170:173], v[194:197], v[56:59]
	v_mfma_f32_16x16x32_bf16 v[44:47], v[142:145], v[202:205], v[44:47]
	v_mfma_f32_16x16x32_bf16 v[40:43], v[170:173], v[202:205], v[40:43]
	v_mfma_f32_16x16x32_bf16 v[28:31], v[142:145], v[210:213], v[28:31]
	v_mfma_f32_16x16x32_bf16 v[24:27], v[170:173], v[210:213], v[24:27]
	v_mfma_f32_16x16x32_bf16 v[12:15], v[142:145], v[224:227], v[12:15]
	v_mfma_f32_16x16x32_bf16 v[8:11], v[170:173], v[224:227], v[8:11]
	v_mfma_f32_16x16x32_bf16 v[60:63], v[146:149], v[198:201], v[60:63]
	v_mfma_f32_16x16x32_bf16 v[56:59], v[174:177], v[198:201], v[56:59]
	v_mfma_f32_16x16x32_bf16 v[44:47], v[146:149], v[206:209], v[44:47]
	v_mfma_f32_16x16x32_bf16 v[40:43], v[174:177], v[206:209], v[40:43]
	v_mfma_f32_16x16x32_bf16 v[28:31], v[146:149], v[220:223], v[28:31]
	v_mfma_f32_16x16x32_bf16 v[24:27], v[174:177], v[220:223], v[24:27]
	v_mfma_f32_16x16x32_bf16 v[12:15], v[146:149], v[228:231], v[12:15]
	v_mfma_f32_16x16x32_bf16 v[8:11], v[174:177], v[228:231], v[8:11]
	s_setprio 0
	s_setprio 1
	v_mfma_f32_16x16x32_bf16 v[52:55], v[178:181], v[194:197], v[52:55]
	v_mfma_f32_16x16x32_bf16 v[48:51], v[186:189], v[194:197], v[48:51]
	v_mfma_f32_16x16x32_bf16 v[36:39], v[178:181], v[202:205], v[36:39]
	v_mfma_f32_16x16x32_bf16 v[32:35], v[186:189], v[202:205], v[32:35]
	v_mfma_f32_16x16x32_bf16 v[20:23], v[178:181], v[210:213], v[20:23]
	v_mfma_f32_16x16x32_bf16 v[16:19], v[186:189], v[210:213], v[16:19]
	v_mfma_f32_16x16x32_bf16 v[4:7], v[178:181], v[224:227], v[4:7]
	v_mfma_f32_16x16x32_bf16 v[0:3], v[186:189], v[224:227], v[0:3]
	v_mfma_f32_16x16x32_bf16 v[52:55], v[182:185], v[198:201], v[52:55]
	v_mfma_f32_16x16x32_bf16 v[48:51], v[190:193], v[198:201], v[48:51]
	v_mfma_f32_16x16x32_bf16 v[36:39], v[182:185], v[206:209], v[36:39]
	v_mfma_f32_16x16x32_bf16 v[32:35], v[190:193], v[206:209], v[32:35]
	v_mfma_f32_16x16x32_bf16 v[20:23], v[182:185], v[220:223], v[20:23]
	v_mfma_f32_16x16x32_bf16 v[16:19], v[190:193], v[220:223], v[16:19]
	v_mfma_f32_16x16x32_bf16 v[4:7], v[182:185], v[228:231], v[4:7]
	v_mfma_f32_16x16x32_bf16 v[0:3], v[190:193], v[228:231], v[0:3]
	s_setprio 0
	s_barrier
	s_add_i32 s44, 0, 0x18000
	s_add_i32 s45, 0, 0x1c000
	v_add_u32_e32 v174, s44, v140
	v_add_u32_e32 v190, s45, v140
	ds_read_b128 v[142:145], v174
	ds_read_b128 v[146:149], v174 offset:1024
	ds_read_b128 v[170:173], v174 offset:2048
	ds_read_b128 v[174:177], v174 offset:3072
	ds_read_b128 v[178:181], v190
	ds_read_b128 v[182:185], v190 offset:1024
	ds_read_b128 v[186:189], v190 offset:2048
	ds_read_b128 v[190:193], v190 offset:3072
	s_add_u32 s38, s38, 0x80000
	s_addc_u32 s39, s39, 0
	s_mov_b32 m0, s28
	v_lshl_add_u64 v[236:237], s[38:39], 0, v[132:133]
	ds_read_b128 v[194:197], v141 offset:32768
	ds_read_b128 v[198:201], v141 offset:33792
	ds_read_b128 v[202:205], v141 offset:34816
	ds_read_b128 v[206:209], v141 offset:35840
	ds_read_b128 v[210:213], v141 offset:36864
	ds_read_b128 v[220:223], v141 offset:37888
	ds_read_b128 v[224:227], v141 offset:38912
	ds_read_b128 v[228:231], v141 offset:39936
	global_load_lds_dwordx4 v[236:237], off
	v_lshl_add_u64 v[236:237], s[38:39], 0, v[130:131]
	s_mov_b32 m0, s29
	s_nop 0
	global_load_lds_dwordx4 v[236:237], off
	s_waitcnt vmcnt(8)
	s_waitcnt lgkmcnt(0)
	s_setprio 1
	s_barrier
	s_waitcnt lgkmcnt(0)
	v_mfma_f32_16x16x32_bf16 v[124:127], v[142:145], v[194:197], v[124:127]
	v_mfma_f32_16x16x32_bf16 v[120:123], v[170:173], v[194:197], v[120:123]
	v_mfma_f32_16x16x32_bf16 v[108:111], v[142:145], v[202:205], v[108:111]
	v_mfma_f32_16x16x32_bf16 v[104:107], v[170:173], v[202:205], v[104:107]
	v_mfma_f32_16x16x32_bf16 v[92:95], v[142:145], v[210:213], v[92:95]
	v_mfma_f32_16x16x32_bf16 v[88:91], v[170:173], v[210:213], v[88:91]
	v_mfma_f32_16x16x32_bf16 v[76:79], v[142:145], v[224:227], v[76:79]
	v_mfma_f32_16x16x32_bf16 v[72:75], v[170:173], v[224:227], v[72:75]
	v_mfma_f32_16x16x32_bf16 v[124:127], v[146:149], v[198:201], v[124:127]
	v_mfma_f32_16x16x32_bf16 v[120:123], v[174:177], v[198:201], v[120:123]
	v_mfma_f32_16x16x32_bf16 v[108:111], v[146:149], v[206:209], v[108:111]
	v_mfma_f32_16x16x32_bf16 v[104:107], v[174:177], v[206:209], v[104:107]
	v_mfma_f32_16x16x32_bf16 v[92:95], v[146:149], v[220:223], v[92:95]
	v_mfma_f32_16x16x32_bf16 v[88:91], v[174:177], v[220:223], v[88:91]
	v_mfma_f32_16x16x32_bf16 v[76:79], v[146:149], v[228:231], v[76:79]
	v_mfma_f32_16x16x32_bf16 v[72:75], v[174:177], v[228:231], v[72:75]
	s_setprio 0
	s_setprio 1
	v_mfma_f32_16x16x32_bf16 v[116:119], v[178:181], v[194:197], v[116:119]
	v_mfma_f32_16x16x32_bf16 v[112:115], v[186:189], v[194:197], v[112:115]
	v_mfma_f32_16x16x32_bf16 v[100:103], v[178:181], v[202:205], v[100:103]
	v_mfma_f32_16x16x32_bf16 v[96:99], v[186:189], v[202:205], v[96:99]
	v_mfma_f32_16x16x32_bf16 v[84:87], v[178:181], v[210:213], v[84:87]
	v_mfma_f32_16x16x32_bf16 v[80:83], v[186:189], v[210:213], v[80:83]
	v_mfma_f32_16x16x32_bf16 v[68:71], v[178:181], v[224:227], v[68:71]
	v_mfma_f32_16x16x32_bf16 v[64:67], v[186:189], v[224:227], v[64:67]
	v_mfma_f32_16x16x32_bf16 v[116:119], v[182:185], v[198:201], v[116:119]
	v_mfma_f32_16x16x32_bf16 v[112:115], v[190:193], v[198:201], v[112:115]
	v_mfma_f32_16x16x32_bf16 v[100:103], v[182:185], v[206:209], v[100:103]
	v_mfma_f32_16x16x32_bf16 v[96:99], v[190:193], v[206:209], v[96:99]
	v_mfma_f32_16x16x32_bf16 v[84:87], v[182:185], v[220:223], v[84:87]
	v_mfma_f32_16x16x32_bf16 v[80:83], v[190:193], v[220:223], v[80:83]
	v_mfma_f32_16x16x32_bf16 v[68:71], v[182:185], v[228:231], v[68:71]
	v_mfma_f32_16x16x32_bf16 v[64:67], v[190:193], v[228:231], v[64:67]
	s_setprio 0
	s_barrier
; #define PG8_STAGE(bufoff, gbase, voff) do { _Pragma("unroll") for (int _i = 0; _i < 2; ++_i) \
;         __builtin_amdgcn_global_load_lds((const unsigned*)((const char*)(gbase) + (voff)[_i]), (PG8_LAS unsigned*)(lds + (bufoff) + ldsw + _i * 8192), 16, 0, 0); } while (0)
; #define PG8_LDA(dst, b, h) do { _Pragma("unroll") for (int m = 0; m < 4; ++m) _Pragma("unroll") for (int k = 0; k < 2; ++k) dst[m][k] = *(const PG8_LAS bf16x8*)(lds + PG8_SA(b, h) + aoff + m * 2048 + k * 1024); } while (0)
; #define PG8_MMA(ai, bj, At, Bt) do { __builtin_amdgcn_s_setprio(1); _Pragma("unroll") for (int m = 0; m < 4; ++m) _Pragma("unroll") for (int n = 0; n < 2; ++n) _Pragma("unroll") for (int k = 0; k < 2; ++k) \
;         acc[ai][bj][m][n] = __builtin_amdgcn_mfma_f32_16x16x32_bf16(Bt[n][k], At[m][k], acc[ai][bj][m][n], 0, 0, 0); __builtin_amdgcn_s_setprio(0); } while (0)
; #define PG8_WAIT_V(n) asm volatile("s_waitcnt vmcnt(" #n ")" ::: "memory")
; #define PG8_WAIT_L(n) asm volatile("s_waitcnt lgkmcnt(" #n ")" ::: "memory")
; #define PG8_BAR __builtin_amdgcn_s_barrier()
; #define PG8_SCHED __builtin_amdgcn_sched_barrier(0)
; template <class Epi, class Sched, bool ALIGN_EPI = false, bool SP2 = false>
; __device__ __forceinline__ void gemm_phase(PG8_LAS unsigned char* lds, const Gemm g, const Sched& S, const Epi& E) {
;     ...
;         for (int t = 0; t < nt; t += 2) {
;             const bool last = (t == nt - 2);
;             const char* a1 = cA + (size_t)(t + 1) * kstep;
;             const char* a2 = last ? nA : cA + (size_t)(t + 2) * kstep; const char* b2 = last ? nB : cB + (size_t)(t + 2) * kstep;
;     ...
;             PG8_WAIT_V(8); PG8_WAIT_L(0); PG8_BAR; PG8_MMA(0, 0, At, B0); PG8_MMA(0, 1, At, B1); PG8_BAR; PG8_SCHED;
;             PG8_LDA(At, 1, 1); PG8_STAGE(PG8_SB(1, 0), b3, voffB); PG8_STAGE(PG8_SB(1, 1), b3 + hstep, voffB); PG8_STAGE(PG8_SA(1, 0), a3, voffA);
;             PG8_WAIT_V(8); PG8_WAIT_L(0); PG8_BAR; PG8_MMA(1, 0, At, B0); PG8_MMA(1, 1, At, B1); PG8_BAR; PG8_SCHED;
	s_add_i32 s38, s44, s26
	v_lshl_add_u64 v[150:151], v[150:151], 0, s[90:91]
	s_mov_b32 m0, s38
	ds_read_b128 v[194:197], v141 offset:49152
	ds_read_b128 v[198:201], v141 offset:50176
	ds_read_b128 v[202:205], v141 offset:51200
	ds_read_b128 v[206:209], v141 offset:52224
	ds_read_b128 v[210:213], v141 offset:53248
	ds_read_b128 v[220:223], v141 offset:54272
	ds_read_b128 v[224:227], v141 offset:55296
	ds_read_b128 v[228:231], v141 offset:56320
	global_load_lds_dwordx4 v[150:151], off
	s_add_i32 m0, s38, 0x2000
	s_add_u32 s18, s18, 0x80080
	v_lshl_add_u64 v[150:151], v[214:215], 0, s[90:91]
	s_addc_u32 s19, s19, 0
	s_add_i32 s38, s45, s26
	global_load_lds_dwordx4 v[150:151], off
	v_lshl_add_u64 v[150:151], s[18:19], 0, v[152:153]
	s_mov_b32 m0, s38
	s_nop 0
	global_load_lds_dwordx4 v[150:151], off
	v_lshl_add_u64 v[150:151], s[18:19], 0, v[128:129]
	s_add_i32 m0, s38, 0x2000
	s_nop 0
	global_load_lds_dwordx4 v[150:151], off
	v_lshl_add_u64 v[150:151], v[232:233], 0, s[90:91]
	s_mov_b32 m0, s33
	s_nop 0
	global_load_lds_dwordx4 v[150:151], off
	v_lshl_add_u64 v[150:151], v[234:235], 0, s[90:91]
	s_mov_b32 m0, s40
	s_nop 0
	global_load_lds_dwordx4 v[150:151], off
	s_waitcnt vmcnt(8)
	s_waitcnt lgkmcnt(0)
	s_setprio 1
	s_barrier
	s_waitcnt lgkmcnt(0)
	v_mfma_f32_16x16x32_bf16 v[60:63], v[142:145], v[194:197], v[60:63]
	v_mfma_f32_16x16x32_bf16 v[56:59], v[170:173], v[194:197], v[56:59]
	v_mfma_f32_16x16x32_bf16 v[44:47], v[142:145], v[202:205], v[44:47]
	v_mfma_f32_16x16x32_bf16 v[40:43], v[170:173], v[202:205], v[40:43]
	v_mfma_f32_16x16x32_bf16 v[28:31], v[142:145], v[210:213], v[28:31]
	v_mfma_f32_16x16x32_bf16 v[24:27], v[170:173], v[210:213], v[24:27]
	v_mfma_f32_16x16x32_bf16 v[12:15], v[142:145], v[224:227], v[12:15]
	v_mfma_f32_16x16x32_bf16 v[8:11], v[170:173], v[224:227], v[8:11]
	v_mfma_f32_16x16x32_bf16 v[60:63], v[146:149], v[198:201], v[60:63]
	v_mfma_f32_16x16x32_bf16 v[56:59], v[174:177], v[198:201], v[56:59]
	v_mfma_f32_16x16x32_bf16 v[44:47], v[146:149], v[206:209], v[44:47]
	v_mfma_f32_16x16x32_bf16 v[40:43], v[174:177], v[206:209], v[40:43]
	v_mfma_f32_16x16x32_bf16 v[28:31], v[146:149], v[220:223], v[28:31]
	v_mfma_f32_16x16x32_bf16 v[24:27], v[174:177], v[220:223], v[24:27]
	v_mfma_f32_16x16x32_bf16 v[12:15], v[146:149], v[228:231], v[12:15]
	v_mfma_f32_16x16x32_bf16 v[8:11], v[174:177], v[228:231], v[8:11]
	s_setprio 0
	s_setprio 1
	v_mfma_f32_16x16x32_bf16 v[52:55], v[178:181], v[194:197], v[52:55]
	v_mfma_f32_16x16x32_bf16 v[48:51], v[186:189], v[194:197], v[48:51]
	v_mfma_f32_16x16x32_bf16 v[36:39], v[178:181], v[202:205], v[36:39]
	v_mfma_f32_16x16x32_bf16 v[32:35], v[186:189], v[202:205], v[32:35]
	v_mfma_f32_16x16x32_bf16 v[20:23], v[178:181], v[210:213], v[20:23]
	v_mfma_f32_16x16x32_bf16 v[16:19], v[186:189], v[210:213], v[16:19]
	v_mfma_f32_16x16x32_bf16 v[4:7], v[178:181], v[224:227], v[4:7]
	v_mfma_f32_16x16x32_bf16 v[0:3], v[186:189], v[224:227], v[0:3]
	v_mfma_f32_16x16x32_bf16 v[52:55], v[182:185], v[198:201], v[52:55]
	v_mfma_f32_16x16x32_bf16 v[48:51], v[190:193], v[198:201], v[48:51]
	v_mfma_f32_16x16x32_bf16 v[36:39], v[182:185], v[206:209], v[36:39]
	v_mfma_f32_16x16x32_bf16 v[32:35], v[190:193], v[206:209], v[32:35]
	v_mfma_f32_16x16x32_bf16 v[20:23], v[182:185], v[220:223], v[20:23]
	v_mfma_f32_16x16x32_bf16 v[16:19], v[190:193], v[220:223], v[16:19]
	v_mfma_f32_16x16x32_bf16 v[4:7], v[182:185], v[228:231], v[4:7]
	v_mfma_f32_16x16x32_bf16 v[0:3], v[190:193], v[228:231], v[0:3]
	s_setprio 0
	s_barrier
	s_add_i32 s43, s43, 2
	s_add_u32 s16, s16, 0x100
	s_addc_u32 s17, s17, 0
	s_cmp_gt_u32 s43, 29
	s_cbranch_scc0 .LBB0_291
	s_cmpk_lt_u32 s25, 0x100
	s_cbranch_scc0 .LBB0_294
	s_barrier

; #define PG8_STAGE(bufoff, gbase, voff) do { _Pragma("unroll") for (int _i = 0; _i < 2; ++_i) \
;         __builtin_amdgcn_global_load_lds((const unsigned*)((const char*)(gbase) + (voff)[_i]), (PG8_LAS unsigned*)(lds + (bufoff) + ldsw + _i * 8192), 16, 0, 0); } while (0)
; #define PG8_LDA(dst, b, h) do { _Pragma("unroll") for (int m = 0; m < 4; ++m) _Pragma("unroll") for (int k = 0; k < 2; ++k) dst[m][k] = *(const PG8_LAS bf16x8*)(lds + PG8_SA(b, h) + aoff + m * 2048 + k * 1024); } while (0)
; #define PG8_LDB(dst, b, h) do { _Pragma("unroll") for (int n = 0; n < 2; ++n) _Pragma("unroll") for (int k = 0; k < 2; ++k) dst[n][k] = *(const PG8_LAS bf16x8*)(lds + PG8_SB(b, h) + boff + n * 2048 + k * 1024); } while (0)
; #define PG8_MMA(ai, bj, At, Bt) do { __builtin_amdgcn_s_setprio(1); _Pragma("unroll") for (int m = 0; m < 4; ++m) _Pragma("unroll") for (int n = 0; n < 2; ++n) _Pragma("unroll") for (int k = 0; k < 2; ++k) \
;         acc[ai][bj][m][n] = __builtin_amdgcn_mfma_f32_16x16x32_bf16(Bt[n][k], At[m][k], acc[ai][bj][m][n], 0, 0, 0); __builtin_amdgcn_s_setprio(0); } while (0)
; #define PG8_WAIT_V(n) asm volatile("s_waitcnt vmcnt(" #n ")" ::: "memory")
; #define PG8_WAIT_L(n) asm volatile("s_waitcnt lgkmcnt(" #n ")" ::: "memory")
; template <class Epi, class Sched, bool ALIGN_EPI = false, bool SP2 = false>
; __device__ __forceinline__ void gemm_phase(PG8_LAS unsigned char* lds, const Gemm g, const Sched& S, const Epi& E) {
;     ...
;             const bool last = (t == nt - 2);
;             const char* a1 = cA + (size_t)(t + 1) * kstep;
;             const char* a2 = last ? nA : cA + (size_t)(t + 2) * kstep; const char* b2 = last ? nB : cB + (size_t)(t + 2) * kstep;
;             const char* a3 = a2 + kstep; const char* b3 = b2 + kstep;
;             if (last && has_next) S.a_ready(nxt);
;             if constexpr (SP2) {
;             PG8_LDB(B0, 0, 0); PG8_LDB(B1, 0, 1); PG8_SCHED; PG8_LDA(At, 0, 0); PG8_STAGE(PG8_SA(1, 1), a1 + hstep, voffA);
;             PG8_WAIT_V(8); PG8_WAIT_L(0); PG8_BAR; PG8_MMA(0, 0, At, B0); PG8_MMA(0, 1, At, B1); PG8_BAR; PG8_SCHED;
;             PG8_LDA(At, 0, 1); PG8_STAGE(PG8_SB(0, 0), b2, voffB); PG8_STAGE(PG8_SB(0, 1), b2 + hstep, voffB); PG8_STAGE(PG8_SA(0, 0), a2, voffA);
;             PG8_WAIT_V(8); PG8_WAIT_L(0); PG8_BAR; PG8_MMA(1, 0, At, B0); PG8_MMA(1, 1, At, B1); PG8_BAR; PG8_SCHED;
.LBB0_349:
	s_or_b32 s4, s48, 1
	s_add_i32 s48, s48, 2
	s_mov_b32 s49, s5
	s_lshl_b64 s[58:59], s[4:5], 7
	s_lshl_b64 s[82:83], s[48:49], 7
	s_add_u32 s4, s14, s82
	s_addc_u32 s33, s15, s83
	s_and_b64 s[56:57], s[54:55], exec
	s_cselect_b32 s57, s45, s33
	s_cselect_b32 s56, s44, s4
	s_add_u32 s4, s16, s82
	s_addc_u32 s33, s17, s83
	s_and_b64 s[54:55], s[54:55], exec
	s_cselect_b32 s55, s47, s33
	s_cselect_b32 s54, s46, s4
	s_add_i32 s4, 0, 0x10000
	v_add_u32_e32 v150, s4, v135
	s_add_i32 s33, 0, 0x14000
	ds_read_b128 v[138:141], v150
	ds_read_b128 v[142:145], v150 offset:1024
	ds_read_b128 v[146:149], v150 offset:2048
	ds_read_b128 v[170:173], v150 offset:3072
	v_add_u32_e32 v150, s33, v135
	ds_read_b128 v[174:177], v150
	ds_read_b128 v[178:181], v150 offset:1024
	ds_read_b128 v[182:185], v150 offset:2048
	ds_read_b128 v[186:189], v150 offset:3072
	s_add_u32 s58, s25, s58
	s_addc_u32 s59, s29, s59
	v_lshl_add_u64 v[150:151], s[58:59], 0, v[128:129]
	s_add_i32 m0, s69, 0xc000
	ds_read_b128 v[190:193], v137
	ds_read_b128 v[194:197], v137 offset:1024
	ds_read_b128 v[198:201], v137 offset:2048
	ds_read_b128 v[202:205], v137 offset:3072
	ds_read_b128 v[206:209], v137 offset:4096
	ds_read_b128 v[210:213], v137 offset:5120
	ds_read_b128 v[220:223], v137 offset:6144
	ds_read_b128 v[224:227], v137 offset:7168
	global_load_lds_dwordx4 v[150:151], off
	v_lshl_add_u64 v[150:151], s[58:59], 0, v[130:131]
	s_add_i32 m0, s69, 0xe000
	s_nop 0
	global_load_lds_dwordx4 v[150:151], off
	s_waitcnt vmcnt(8)
	s_waitcnt lgkmcnt(0)
	s_setprio 1
	s_barrier
	s_waitcnt lgkmcnt(0)
	v_mfma_f32_16x16x32_bf16 v[124:127], v[138:141], v[190:193], v[124:127]
	v_mfma_f32_16x16x32_bf16 v[120:123], v[146:149], v[190:193], v[120:123]
	v_mfma_f32_16x16x32_bf16 v[116:119], v[138:141], v[198:201], v[116:119]
	v_mfma_f32_16x16x32_bf16 v[112:115], v[146:149], v[198:201], v[112:115]
	v_mfma_f32_16x16x32_bf16 v[108:111], v[138:141], v[206:209], v[108:111]
	v_mfma_f32_16x16x32_bf16 v[104:107], v[146:149], v[206:209], v[104:107]
	v_mfma_f32_16x16x32_bf16 v[100:103], v[138:141], v[220:223], v[100:103]
	v_mfma_f32_16x16x32_bf16 v[96:99], v[146:149], v[220:223], v[96:99]
	v_mfma_f32_16x16x32_bf16 v[124:127], v[142:145], v[194:197], v[124:127]
	v_mfma_f32_16x16x32_bf16 v[120:123], v[170:173], v[194:197], v[120:123]
	v_mfma_f32_16x16x32_bf16 v[116:119], v[142:145], v[202:205], v[116:119]
	v_mfma_f32_16x16x32_bf16 v[112:115], v[170:173], v[202:205], v[112:115]
	v_mfma_f32_16x16x32_bf16 v[108:111], v[142:145], v[210:213], v[108:111]
	v_mfma_f32_16x16x32_bf16 v[104:107], v[170:173], v[210:213], v[104:107]
	v_mfma_f32_16x16x32_bf16 v[100:103], v[142:145], v[224:227], v[100:103]
	v_mfma_f32_16x16x32_bf16 v[96:99], v[170:173], v[224:227], v[96:99]
	s_setprio 0
	s_setprio 1
	v_mfma_f32_16x16x32_bf16 v[92:95], v[174:177], v[190:193], v[92:95]
	v_mfma_f32_16x16x32_bf16 v[88:91], v[182:185], v[190:193], v[88:91]
	v_mfma_f32_16x16x32_bf16 v[84:87], v[174:177], v[198:201], v[84:87]
	v_mfma_f32_16x16x32_bf16 v[80:83], v[182:185], v[198:201], v[80:83]
	v_mfma_f32_16x16x32_bf16 v[76:79], v[174:177], v[206:209], v[76:79]
	v_mfma_f32_16x16x32_bf16 v[72:75], v[182:185], v[206:209], v[72:75]
	v_mfma_f32_16x16x32_bf16 v[68:71], v[174:177], v[220:223], v[68:71]
	v_mfma_f32_16x16x32_bf16 v[64:67], v[182:185], v[220:223], v[64:67]
	v_mfma_f32_16x16x32_bf16 v[92:95], v[178:181], v[194:197], v[92:95]
	v_mfma_f32_16x16x32_bf16 v[88:91], v[186:189], v[194:197], v[88:91]
	v_mfma_f32_16x16x32_bf16 v[84:87], v[178:181], v[202:205], v[84:87]
	v_mfma_f32_16x16x32_bf16 v[80:83], v[186:189], v[202:205], v[80:83]
	v_mfma_f32_16x16x32_bf16 v[76:79], v[178:181], v[210:213], v[76:79]
	v_mfma_f32_16x16x32_bf16 v[72:75], v[186:189], v[210:213], v[72:75]
	v_mfma_f32_16x16x32_bf16 v[68:71], v[178:181], v[224:227], v[68:71]
	v_mfma_f32_16x16x32_bf16 v[64:67], v[186:189], v[224:227], v[64:67]
	s_setprio 0
	s_barrier
	s_add_i32 s4, s4, s68
	v_lshl_add_u64 v[150:151], s[54:55], 0, v[152:153]
	s_mov_b32 m0, s4
	ds_read_b128 v[190:193], v137 offset:16384
	ds_read_b128 v[194:197], v137 offset:17408
	ds_read_b128 v[198:201], v137 offset:18432
	ds_read_b128 v[202:205], v137 offset:19456
	ds_read_b128 v[206:209], v137 offset:20480
	ds_read_b128 v[210:213], v137 offset:21504
	ds_read_b128 v[220:223], v137 offset:22528
	ds_read_b128 v[224:227], v137 offset:23552
	global_load_lds_dwordx4 v[150:151], off
	s_add_i32 m0, s4, 0x2000
	v_lshl_add_u64 v[214:215], s[54:55], 0, v[132:133]
	s_add_u32 s54, s54, s66
	s_addc_u32 s55, s55, 0
	s_add_i32 s4, s33, s68
	global_load_lds_dwordx4 v[214:215], off
	v_lshl_add_u64 v[228:229], s[54:55], 0, v[152:153]
	s_mov_b32 m0, s4
	v_lshl_add_u64 v[230:231], s[54:55], 0, v[132:133]
	global_load_lds_dwordx4 v[228:229], off
	s_add_i32 m0, s4, 0x2000
	v_lshl_add_u64 v[232:233], s[56:57], 0, v[128:129]
	global_load_lds_dwordx4 v[230:231], off
	s_mov_b32 m0, s69
	v_lshl_add_u64 v[234:235], s[56:57], 0, v[130:131]
	global_load_lds_dwordx4 v[232:233], off
	s_mov_b32 m0, s70
	s_nop 0
	global_load_lds_dwordx4 v[234:235], off
	s_waitcnt vmcnt(8)
	s_waitcnt lgkmcnt(0)
	s_setprio 1
	s_barrier
; #define PG8_STAGE(bufoff, gbase, voff) do { _Pragma("unroll") for (int _i = 0; _i < 2; ++_i) \
;         __builtin_amdgcn_global_load_lds((const unsigned*)((const char*)(gbase) + (voff)[_i]), (PG8_LAS unsigned*)(lds + (bufoff) + ldsw + _i * 8192), 16, 0, 0); } while (0)
; #define PG8_LDA(dst, b, h) do { _Pragma("unroll") for (int m = 0; m < 4; ++m) _Pragma("unroll") for (int k = 0; k < 2; ++k) dst[m][k] = *(const PG8_LAS bf16x8*)(lds + PG8_SA(b, h) + aoff + m * 2048 + k * 1024); } while (0)
; #define PG8_LDB(dst, b, h) do { _Pragma("unroll") for (int n = 0; n < 2; ++n) _Pragma("unroll") for (int k = 0; k < 2; ++k) dst[n][k] = *(const PG8_LAS bf16x8*)(lds + PG8_SB(b, h) + boff + n * 2048 + k * 1024); } while (0)
; #define PG8_MMA(ai, bj, At, Bt) do { __builtin_amdgcn_s_setprio(1); _Pragma("unroll") for (int m = 0; m < 4; ++m) _Pragma("unroll") for (int n = 0; n < 2; ++n) _Pragma("unroll") for (int k = 0; k < 2; ++k) \
;         acc[ai][bj][m][n] = __builtin_amdgcn_mfma_f32_16x16x32_bf16(Bt[n][k], At[m][k], acc[ai][bj][m][n], 0, 0, 0); __builtin_amdgcn_s_setprio(0); } while (0)
; #define PG8_WAIT_V(n) asm volatile("s_waitcnt vmcnt(" #n ")" ::: "memory")
; #define PG8_WAIT_L(n) asm volatile("s_waitcnt lgkmcnt(" #n ")" ::: "memory")
; #define PG8_BAR __builtin_amdgcn_s_barrier()
; #define PG8_SCHED __builtin_amdgcn_sched_barrier(0)
; template <class Epi, class Sched, bool ALIGN_EPI = false, bool SP2 = false>
; __device__ __forceinline__ void gemm_phase(PG8_LAS unsigned char* lds, const Gemm g, const Sched& S, const Epi& E) {
;     ...
;             PG8_WAIT_V(8); PG8_WAIT_L(0); PG8_BAR; PG8_MMA(1, 0, At, B0); PG8_MMA(1, 1, At, B1); PG8_BAR; PG8_SCHED;
;             PG8_LDB(B0, 1, 0); PG8_LDB(B1, 1, 1); PG8_SCHED; PG8_LDA(At, 1, 0); PG8_STAGE(PG8_SA(0, 1), a2 + hstep, voffA);
;             PG8_WAIT_V(8); PG8_WAIT_L(0); PG8_BAR; PG8_MMA(0, 0, At, B0); PG8_MMA(0, 1, At, B1); PG8_BAR; PG8_SCHED;
	s_waitcnt lgkmcnt(0)
	v_mfma_f32_16x16x32_bf16 v[60:63], v[138:141], v[190:193], v[60:63]
	v_mfma_f32_16x16x32_bf16 v[56:59], v[146:149], v[190:193], v[56:59]
	v_mfma_f32_16x16x32_bf16 v[52:55], v[138:141], v[198:201], v[52:55]
	v_mfma_f32_16x16x32_bf16 v[48:51], v[146:149], v[198:201], v[48:51]
	v_mfma_f32_16x16x32_bf16 v[44:47], v[138:141], v[206:209], v[44:47]
	v_mfma_f32_16x16x32_bf16 v[40:43], v[146:149], v[206:209], v[40:43]
	v_mfma_f32_16x16x32_bf16 v[36:39], v[138:141], v[220:223], v[36:39]
	v_mfma_f32_16x16x32_bf16 v[32:35], v[146:149], v[220:223], v[32:35]
	v_mfma_f32_16x16x32_bf16 v[60:63], v[142:145], v[194:197], v[60:63]
	v_mfma_f32_16x16x32_bf16 v[56:59], v[170:173], v[194:197], v[56:59]
	v_mfma_f32_16x16x32_bf16 v[52:55], v[142:145], v[202:205], v[52:55]
	v_mfma_f32_16x16x32_bf16 v[48:51], v[170:173], v[202:205], v[48:51]
	v_mfma_f32_16x16x32_bf16 v[44:47], v[142:145], v[210:213], v[44:47]
	v_mfma_f32_16x16x32_bf16 v[40:43], v[170:173], v[210:213], v[40:43]
	v_mfma_f32_16x16x32_bf16 v[36:39], v[142:145], v[224:227], v[36:39]
	v_mfma_f32_16x16x32_bf16 v[32:35], v[170:173], v[224:227], v[32:35]
	s_setprio 0
	s_setprio 1
	v_mfma_f32_16x16x32_bf16 v[28:31], v[174:177], v[190:193], v[28:31]
	v_mfma_f32_16x16x32_bf16 v[24:27], v[182:185], v[190:193], v[24:27]
	v_mfma_f32_16x16x32_bf16 v[20:23], v[174:177], v[198:201], v[20:23]
	v_mfma_f32_16x16x32_bf16 v[16:19], v[182:185], v[198:201], v[16:19]
	v_mfma_f32_16x16x32_bf16 v[12:15], v[174:177], v[206:209], v[12:15]
	v_mfma_f32_16x16x32_bf16 v[8:11], v[182:185], v[206:209], v[8:11]
	v_mfma_f32_16x16x32_bf16 v[4:7], v[174:177], v[220:223], v[4:7]
	v_mfma_f32_16x16x32_bf16 v[0:3], v[182:185], v[220:223], v[0:3]
	v_mfma_f32_16x16x32_bf16 v[28:31], v[178:181], v[194:197], v[28:31]
	v_mfma_f32_16x16x32_bf16 v[24:27], v[186:189], v[194:197], v[24:27]
	v_mfma_f32_16x16x32_bf16 v[20:23], v[178:181], v[202:205], v[20:23]
	v_mfma_f32_16x16x32_bf16 v[16:19], v[186:189], v[202:205], v[16:19]
	v_mfma_f32_16x16x32_bf16 v[12:15], v[178:181], v[210:213], v[12:15]
	v_mfma_f32_16x16x32_bf16 v[8:11], v[186:189], v[210:213], v[8:11]
	v_mfma_f32_16x16x32_bf16 v[4:7], v[178:181], v[224:227], v[4:7]
	v_mfma_f32_16x16x32_bf16 v[0:3], v[186:189], v[224:227], v[0:3]
	s_setprio 0
	s_barrier
	s_add_i32 s4, 0, 0x18000
	s_add_i32 s33, 0, 0x1c000
	v_add_u32_e32 v170, s4, v135
	v_add_u32_e32 v186, s33, v135
	ds_read_b128 v[138:141], v170
	ds_read_b128 v[142:145], v170 offset:1024
	ds_read_b128 v[146:149], v170 offset:2048
	ds_read_b128 v[170:173], v170 offset:3072
	ds_read_b128 v[174:177], v186
	ds_read_b128 v[178:181], v186 offset:1024
	ds_read_b128 v[182:185], v186 offset:2048
	ds_read_b128 v[186:189], v186 offset:3072
	s_add_u32 s54, s56, s66
	s_addc_u32 s55, s57, 0
	s_mov_b32 m0, s71
	v_lshl_add_u64 v[236:237], s[54:55], 0, v[128:129]
	ds_read_b128 v[190:193], v137 offset:32768
	ds_read_b128 v[194:197], v137 offset:33792
	ds_read_b128 v[198:201], v137 offset:34816
	ds_read_b128 v[202:205], v137 offset:35840
	ds_read_b128 v[206:209], v137 offset:36864
	ds_read_b128 v[210:213], v137 offset:37888
	ds_read_b128 v[220:223], v137 offset:38912
	ds_read_b128 v[224:227], v137 offset:39936
	global_load_lds_dwordx4 v[236:237], off
	v_lshl_add_u64 v[236:237], s[54:55], 0, v[130:131]
	s_mov_b32 m0, s72
	s_nop 0
	global_load_lds_dwordx4 v[236:237], off
	s_waitcnt vmcnt(8)
	s_waitcnt lgkmcnt(0)
	s_setprio 1
	s_barrier
	s_waitcnt lgkmcnt(0)
	v_mfma_f32_16x16x32_bf16 v[124:127], v[138:141], v[190:193], v[124:127]
	v_mfma_f32_16x16x32_bf16 v[120:123], v[146:149], v[190:193], v[120:123]
	v_mfma_f32_16x16x32_bf16 v[116:119], v[138:141], v[198:201], v[116:119]
	v_mfma_f32_16x16x32_bf16 v[112:115], v[146:149], v[198:201], v[112:115]
	v_mfma_f32_16x16x32_bf16 v[108:111], v[138:141], v[206:209], v[108:111]
	v_mfma_f32_16x16x32_bf16 v[104:107], v[146:149], v[206:209], v[104:107]
	v_mfma_f32_16x16x32_bf16 v[100:103], v[138:141], v[220:223], v[100:103]
	v_mfma_f32_16x16x32_bf16 v[96:99], v[146:149], v[220:223], v[96:99]
	v_mfma_f32_16x16x32_bf16 v[124:127], v[142:145], v[194:197], v[124:127]
	v_mfma_f32_16x16x32_bf16 v[120:123], v[170:173], v[194:197], v[120:123]
	v_mfma_f32_16x16x32_bf16 v[116:119], v[142:145], v[202:205], v[116:119]
	v_mfma_f32_16x16x32_bf16 v[112:115], v[170:173], v[202:205], v[112:115]
	v_mfma_f32_16x16x32_bf16 v[108:111], v[142:145], v[210:213], v[108:111]
	v_mfma_f32_16x16x32_bf16 v[104:107], v[170:173], v[210:213], v[104:107]
	v_mfma_f32_16x16x32_bf16 v[100:103], v[142:145], v[224:227], v[100:103]
	v_mfma_f32_16x16x32_bf16 v[96:99], v[170:173], v[224:227], v[96:99]
	s_setprio 0
	s_setprio 1
	v_mfma_f32_16x16x32_bf16 v[92:95], v[174:177], v[190:193], v[92:95]
	v_mfma_f32_16x16x32_bf16 v[88:91], v[182:185], v[190:193], v[88:91]
	v_mfma_f32_16x16x32_bf16 v[84:87], v[174:177], v[198:201], v[84:87]
	v_mfma_f32_16x16x32_bf16 v[80:83], v[182:185], v[198:201], v[80:83]
	v_mfma_f32_16x16x32_bf16 v[76:79], v[174:177], v[206:209], v[76:79]
	v_mfma_f32_16x16x32_bf16 v[72:75], v[182:185], v[206:209], v[72:75]
	v_mfma_f32_16x16x32_bf16 v[68:71], v[174:177], v[220:223], v[68:71]
	v_mfma_f32_16x16x32_bf16 v[64:67], v[182:185], v[220:223], v[64:67]
	v_mfma_f32_16x16x32_bf16 v[92:95], v[178:181], v[194:197], v[92:95]
	v_mfma_f32_16x16x32_bf16 v[88:91], v[186:189], v[194:197], v[88:91]
	v_mfma_f32_16x16x32_bf16 v[84:87], v[178:181], v[202:205], v[84:87]
	v_mfma_f32_16x16x32_bf16 v[80:83], v[186:189], v[202:205], v[80:83]
	v_mfma_f32_16x16x32_bf16 v[76:79], v[178:181], v[210:213], v[76:79]
	v_mfma_f32_16x16x32_bf16 v[72:75], v[186:189], v[210:213], v[72:75]
	v_mfma_f32_16x16x32_bf16 v[68:71], v[178:181], v[224:227], v[68:71]
	v_mfma_f32_16x16x32_bf16 v[64:67], v[186:189], v[224:227], v[64:67]
	s_setprio 0
	s_barrier
; #define PG8_STAGE(bufoff, gbase, voff) do { _Pragma("unroll") for (int _i = 0; _i < 2; ++_i) \
;         __builtin_amdgcn_global_load_lds((const unsigned*)((const char*)(gbase) + (voff)[_i]), (PG8_LAS unsigned*)(lds + (bufoff) + ldsw + _i * 8192), 16, 0, 0); } while (0)
; #define PG8_LDA(dst, b, h) do { _Pragma("unroll") for (int m = 0; m < 4; ++m) _Pragma("unroll") for (int k = 0; k < 2; ++k) dst[m][k] = *(const PG8_LAS bf16x8*)(lds + PG8_SA(b, h) + aoff + m * 2048 + k * 1024); } while (0)
; #define PG8_MMA(ai, bj, At, Bt) do { __builtin_amdgcn_s_setprio(1); _Pragma("unroll") for (int m = 0; m < 4; ++m) _Pragma("unroll") for (int n = 0; n < 2; ++n) _Pragma("unroll") for (int k = 0; k < 2; ++k) \
;         acc[ai][bj][m][n] = __builtin_amdgcn_mfma_f32_16x16x32_bf16(Bt[n][k], At[m][k], acc[ai][bj][m][n], 0, 0, 0); __builtin_amdgcn_s_setprio(0); } while (0)
; #define PG8_WAIT_V(n) asm volatile("s_waitcnt vmcnt(" #n ")" ::: "memory")
; #define PG8_WAIT_L(n) asm volatile("s_waitcnt lgkmcnt(" #n ")" ::: "memory")
; #define PG8_BAR __builtin_amdgcn_s_barrier()
; #define PG8_SCHED __builtin_amdgcn_sched_barrier(0)
; template <class Epi, class Sched, bool ALIGN_EPI = false, bool SP2 = false>
; __device__ __forceinline__ void gemm_phase(PG8_LAS unsigned char* lds, const Gemm g, const Sched& S, const Epi& E) {
;     ...
;         for (int t = 0; t < nt; t += 2) {
;             const bool last = (t == nt - 2);
;             const char* a1 = cA + (size_t)(t + 1) * kstep;
;             const char* a2 = last ? nA : cA + (size_t)(t + 2) * kstep; const char* b2 = last ? nB : cB + (size_t)(t + 2) * kstep;
;     ...
;             PG8_WAIT_V(8); PG8_WAIT_L(0); PG8_BAR; PG8_MMA(0, 0, At, B0); PG8_MMA(0, 1, At, B1); PG8_BAR; PG8_SCHED;
;             PG8_LDA(At, 1, 1); PG8_STAGE(PG8_SB(1, 0), b3, voffB); PG8_STAGE(PG8_SB(1, 1), b3 + hstep, voffB); PG8_STAGE(PG8_SA(1, 0), a3, voffA);
;             PG8_WAIT_V(8); PG8_WAIT_L(0); PG8_BAR; PG8_MMA(1, 0, At, B0); PG8_MMA(1, 1, At, B1); PG8_BAR; PG8_SCHED;
	s_add_i32 s4, s4, s68
	v_lshl_add_u64 v[150:151], v[150:151], 0, s[90:91]
	s_mov_b32 m0, s4
	ds_read_b128 v[190:193], v137 offset:49152
	ds_read_b128 v[194:197], v137 offset:50176
	ds_read_b128 v[198:201], v137 offset:51200
	ds_read_b128 v[202:205], v137 offset:52224
	ds_read_b128 v[206:209], v137 offset:53248
	ds_read_b128 v[210:213], v137 offset:54272
	ds_read_b128 v[220:223], v137 offset:55296
	ds_read_b128 v[224:227], v137 offset:56320
	global_load_lds_dwordx4 v[150:151], off
	v_lshl_add_u64 v[150:151], v[214:215], 0, s[90:91]
	s_add_i32 m0, s4, 0x2000
	s_add_i32 s4, s33, s68
	global_load_lds_dwordx4 v[150:151], off
	v_lshl_add_u64 v[150:151], v[228:229], 0, s[90:91]
	s_mov_b32 m0, s4
	s_nop 0
	global_load_lds_dwordx4 v[150:151], off
	v_lshl_add_u64 v[150:151], v[230:231], 0, s[90:91]
	s_add_i32 m0, s4, 0x2000
	s_nop 0
	global_load_lds_dwordx4 v[150:151], off
	v_lshl_add_u64 v[150:151], v[232:233], 0, s[90:91]
	s_mov_b32 m0, s75
	s_nop 0
	global_load_lds_dwordx4 v[150:151], off
	v_lshl_add_u64 v[150:151], v[234:235], 0, s[90:91]
	s_mov_b32 m0, s76
	s_nop 0
	global_load_lds_dwordx4 v[150:151], off
	s_waitcnt vmcnt(8)
	s_waitcnt lgkmcnt(0)
	s_setprio 1
	s_barrier
	s_waitcnt lgkmcnt(0)
	v_mfma_f32_16x16x32_bf16 v[60:63], v[138:141], v[190:193], v[60:63]
	v_mfma_f32_16x16x32_bf16 v[56:59], v[146:149], v[190:193], v[56:59]
	v_mfma_f32_16x16x32_bf16 v[52:55], v[138:141], v[198:201], v[52:55]
	v_mfma_f32_16x16x32_bf16 v[48:51], v[146:149], v[198:201], v[48:51]
	v_mfma_f32_16x16x32_bf16 v[44:47], v[138:141], v[206:209], v[44:47]
	v_mfma_f32_16x16x32_bf16 v[40:43], v[146:149], v[206:209], v[40:43]
	v_mfma_f32_16x16x32_bf16 v[36:39], v[138:141], v[220:223], v[36:39]
	v_mfma_f32_16x16x32_bf16 v[32:35], v[146:149], v[220:223], v[32:35]
	v_mfma_f32_16x16x32_bf16 v[60:63], v[142:145], v[194:197], v[60:63]
	v_mfma_f32_16x16x32_bf16 v[56:59], v[170:173], v[194:197], v[56:59]
	v_mfma_f32_16x16x32_bf16 v[52:55], v[142:145], v[202:205], v[52:55]
	v_mfma_f32_16x16x32_bf16 v[48:51], v[170:173], v[202:205], v[48:51]
	v_mfma_f32_16x16x32_bf16 v[44:47], v[142:145], v[210:213], v[44:47]
	v_mfma_f32_16x16x32_bf16 v[40:43], v[170:173], v[210:213], v[40:43]
	v_mfma_f32_16x16x32_bf16 v[36:39], v[142:145], v[224:227], v[36:39]
	v_mfma_f32_16x16x32_bf16 v[32:35], v[170:173], v[224:227], v[32:35]
	s_setprio 0
	s_setprio 1
	v_mfma_f32_16x16x32_bf16 v[28:31], v[174:177], v[190:193], v[28:31]
	v_mfma_f32_16x16x32_bf16 v[24:27], v[182:185], v[190:193], v[24:27]
	v_mfma_f32_16x16x32_bf16 v[20:23], v[174:177], v[198:201], v[20:23]
	v_mfma_f32_16x16x32_bf16 v[16:19], v[182:185], v[198:201], v[16:19]
	v_mfma_f32_16x16x32_bf16 v[12:15], v[174:177], v[206:209], v[12:15]
	v_mfma_f32_16x16x32_bf16 v[8:11], v[182:185], v[206:209], v[8:11]
	v_mfma_f32_16x16x32_bf16 v[4:7], v[174:177], v[220:223], v[4:7]
	v_mfma_f32_16x16x32_bf16 v[0:3], v[182:185], v[220:223], v[0:3]
	v_mfma_f32_16x16x32_bf16 v[28:31], v[178:181], v[194:197], v[28:31]
	v_mfma_f32_16x16x32_bf16 v[24:27], v[186:189], v[194:197], v[24:27]
	v_mfma_f32_16x16x32_bf16 v[20:23], v[178:181], v[202:205], v[20:23]
	v_mfma_f32_16x16x32_bf16 v[16:19], v[186:189], v[202:205], v[16:19]
	v_mfma_f32_16x16x32_bf16 v[12:15], v[178:181], v[210:213], v[12:15]
	v_mfma_f32_16x16x32_bf16 v[8:11], v[186:189], v[210:213], v[8:11]
	v_mfma_f32_16x16x32_bf16 v[4:7], v[178:181], v[224:227], v[4:7]
	v_mfma_f32_16x16x32_bf16 v[0:3], v[186:189], v[224:227], v[0:3]
	s_setprio 0
	s_barrier
	s_cmp_ge_u32 s48, s73
	s_cbranch_scc1 .LBB0_356

; #define PG8_STAGE(bufoff, gbase, voff) do { _Pragma("unroll") for (int _i = 0; _i < 2; ++_i) \
;         __builtin_amdgcn_global_load_lds((const unsigned*)((const char*)(gbase) + (voff)[_i]), (PG8_LAS unsigned*)(lds + (bufoff) + ldsw + _i * 8192), 16, 0, 0); } while (0)
; #define PG8_LDA(dst, b, h) do { _Pragma("unroll") for (int m = 0; m < 4; ++m) _Pragma("unroll") for (int k = 0; k < 2; ++k) dst[m][k] = *(const PG8_LAS bf16x8*)(lds + PG8_SA(b, h) + aoff + m * 2048 + k * 1024); } while (0)
; #define PG8_LDB(dst, b, h) do { _Pragma("unroll") for (int n = 0; n < 2; ++n) _Pragma("unroll") for (int k = 0; k < 2; ++k) dst[n][k] = *(const PG8_LAS bf16x8*)(lds + PG8_SB(b, h) + boff + n * 2048 + k * 1024); } while (0)
; #define PG8_MMA(ai, bj, At, Bt) do { __builtin_amdgcn_s_setprio(1); _Pragma("unroll") for (int m = 0; m < 4; ++m) _Pragma("unroll") for (int n = 0; n < 2; ++n) _Pragma("unroll") for (int k = 0; k < 2; ++k) \
;         acc[ai][bj][m][n] = __builtin_amdgcn_mfma_f32_16x16x32_bf16(Bt[n][k], At[m][k], acc[ai][bj][m][n], 0, 0, 0); __builtin_amdgcn_s_setprio(0); } while (0)
; #define PG8_WAIT_V(n) asm volatile("s_waitcnt vmcnt(" #n ")" ::: "memory")
; #define PG8_WAIT_L(n) asm volatile("s_waitcnt lgkmcnt(" #n ")" ::: "memory")
; template <class Epi, class Sched, bool ALIGN_EPI = false, bool SP2 = false>
; __device__ __forceinline__ void gemm_phase(PG8_LAS unsigned char* lds, const Gemm g, const Sched& S, const Epi& E) {
;     ...
;             const bool last = (t == nt - 2);
;             const char* a1 = cA + (size_t)(t + 1) * kstep;
;             const char* a2 = last ? nA : cA + (size_t)(t + 2) * kstep; const char* b2 = last ? nB : cB + (size_t)(t + 2) * kstep;
;             const char* a3 = a2 + kstep; const char* b3 = b2 + kstep;
;             if (last && has_next) S.a_ready(nxt);
;             if constexpr (SP2) {
;             PG8_LDB(B0, 0, 0); PG8_LDB(B1, 0, 1); PG8_SCHED; PG8_LDA(At, 0, 0); PG8_STAGE(PG8_SA(1, 1), a1 + hstep, voffA);
;             PG8_WAIT_V(8); PG8_WAIT_L(0); PG8_BAR; PG8_MMA(0, 0, At, B0); PG8_MMA(0, 1, At, B1); PG8_BAR; PG8_SCHED;
;             PG8_LDA(At, 0, 1); PG8_STAGE(PG8_SB(0, 0), b2, voffB); PG8_STAGE(PG8_SB(0, 1), b2 + hstep, voffB); PG8_STAGE(PG8_SA(0, 0), a2, voffA);
;             PG8_WAIT_V(8); PG8_WAIT_L(0); PG8_BAR; PG8_MMA(1, 0, At, B0); PG8_MMA(1, 1, At, B1); PG8_BAR; PG8_SCHED;
.LBB0_431:
	s_add_u32 s54, s42, s52
	s_addc_u32 s55, s43, s53
	s_add_u32 s54, s54, 0x100
	s_addc_u32 s55, s55, 0
	s_add_u32 s75, s29, s52
	s_addc_u32 s76, s33, s53
	s_cmpk_eq_i32 s52, 0xf00
	s_cselect_b32 s57, s25, s55
	s_cselect_b32 s56, s47, s54
	s_cselect_b32 s55, s45, s76
	s_cselect_b32 s54, s73, s75
	s_add_i32 s75, 0, 0x10000
	v_add_u32_e32 v152, s75, v145
	s_add_i32 s78, 0, 0x14000
	ds_read_b128 v[148:151], v152
	ds_read_b128 v[170:173], v152 offset:1024
	ds_read_b128 v[174:177], v152 offset:2048
	ds_read_b128 v[178:181], v152 offset:3072
	v_add_u32_e32 v152, s78, v145
	ds_read_b128 v[182:185], v152
	ds_read_b128 v[186:189], v152 offset:1024
	ds_read_b128 v[190:193], v152 offset:2048
	ds_read_b128 v[194:197], v152 offset:3072
	v_lshl_add_u64 v[214:215], v[140:141], 0, s[52:53]
	s_add_i32 m0, s15, 0xc000
	ds_read_b128 v[198:201], v147
	ds_read_b128 v[202:205], v147 offset:1024
	ds_read_b128 v[206:209], v147 offset:2048
	ds_read_b128 v[210:213], v147 offset:3072
	ds_read_b128 v[220:223], v147 offset:4096
	ds_read_b128 v[224:227], v147 offset:5120
	ds_read_b128 v[228:231], v147 offset:6144
	ds_read_b128 v[232:235], v147 offset:7168
	global_load_lds_dwordx4 v[214:215], off
	v_lshl_add_u64 v[214:215], v[142:143], 0, s[52:53]
	s_add_i32 m0, s15, 0xe000
	s_nop 0
	global_load_lds_dwordx4 v[214:215], off
	s_waitcnt vmcnt(8)
	s_waitcnt lgkmcnt(0)
	s_setprio 1
	s_barrier
	s_waitcnt lgkmcnt(0)
	v_mfma_f32_16x16x32_bf16 v[124:127], v[148:151], v[198:201], v[124:127]
	v_mfma_f32_16x16x32_bf16 v[120:123], v[174:177], v[198:201], v[120:123]
	v_mfma_f32_16x16x32_bf16 v[116:119], v[148:151], v[206:209], v[116:119]
	v_mfma_f32_16x16x32_bf16 v[112:115], v[174:177], v[206:209], v[112:115]
	v_mfma_f32_16x16x32_bf16 v[108:111], v[148:151], v[220:223], v[108:111]
	v_mfma_f32_16x16x32_bf16 v[104:107], v[174:177], v[220:223], v[104:107]
	v_mfma_f32_16x16x32_bf16 v[100:103], v[148:151], v[228:231], v[100:103]
	v_mfma_f32_16x16x32_bf16 v[96:99], v[174:177], v[228:231], v[96:99]
	v_mfma_f32_16x16x32_bf16 v[124:127], v[170:173], v[202:205], v[124:127]
	v_mfma_f32_16x16x32_bf16 v[120:123], v[178:181], v[202:205], v[120:123]
	v_mfma_f32_16x16x32_bf16 v[116:119], v[170:173], v[210:213], v[116:119]
	v_mfma_f32_16x16x32_bf16 v[112:115], v[178:181], v[210:213], v[112:115]
	v_mfma_f32_16x16x32_bf16 v[108:111], v[170:173], v[224:227], v[108:111]
	v_mfma_f32_16x16x32_bf16 v[104:107], v[178:181], v[224:227], v[104:107]
	v_mfma_f32_16x16x32_bf16 v[100:103], v[170:173], v[232:235], v[100:103]
	v_mfma_f32_16x16x32_bf16 v[96:99], v[178:181], v[232:235], v[96:99]
	s_setprio 0
	s_setprio 1
	v_mfma_f32_16x16x32_bf16 v[92:95], v[182:185], v[198:201], v[92:95]
	v_mfma_f32_16x16x32_bf16 v[88:91], v[190:193], v[198:201], v[88:91]
	v_mfma_f32_16x16x32_bf16 v[84:87], v[182:185], v[206:209], v[84:87]
	v_mfma_f32_16x16x32_bf16 v[80:83], v[190:193], v[206:209], v[80:83]
	v_mfma_f32_16x16x32_bf16 v[76:79], v[182:185], v[220:223], v[76:79]
	v_mfma_f32_16x16x32_bf16 v[72:75], v[190:193], v[220:223], v[72:75]
	v_mfma_f32_16x16x32_bf16 v[68:71], v[182:185], v[228:231], v[68:71]
	v_mfma_f32_16x16x32_bf16 v[64:67], v[190:193], v[228:231], v[64:67]
	v_mfma_f32_16x16x32_bf16 v[92:95], v[186:189], v[202:205], v[92:95]
	v_mfma_f32_16x16x32_bf16 v[88:91], v[194:197], v[202:205], v[88:91]
	v_mfma_f32_16x16x32_bf16 v[84:87], v[186:189], v[210:213], v[84:87]
	v_mfma_f32_16x16x32_bf16 v[80:83], v[194:197], v[210:213], v[80:83]
	v_mfma_f32_16x16x32_bf16 v[76:79], v[186:189], v[224:227], v[76:79]
	v_mfma_f32_16x16x32_bf16 v[72:75], v[194:197], v[224:227], v[72:75]
	v_mfma_f32_16x16x32_bf16 v[68:71], v[186:189], v[232:235], v[68:71]
	v_mfma_f32_16x16x32_bf16 v[64:67], v[194:197], v[232:235], v[64:67]
	s_setprio 0
	s_barrier
	s_add_i32 s75, s75, s65
	v_lshl_add_u64 v[214:215], s[54:55], 0, v[130:131]
	s_mov_b32 m0, s75
	ds_read_b128 v[198:201], v147 offset:16384
	ds_read_b128 v[202:205], v147 offset:17408
	ds_read_b128 v[206:209], v147 offset:18432
	ds_read_b128 v[210:213], v147 offset:19456
	ds_read_b128 v[220:223], v147 offset:20480
	ds_read_b128 v[224:227], v147 offset:21504
	ds_read_b128 v[228:231], v147 offset:22528
	ds_read_b128 v[232:235], v147 offset:23552
	global_load_lds_dwordx4 v[214:215], off
	s_add_i32 m0, s75, 0x2000
	s_add_u32 s76, s54, 0x80000
	v_lshl_add_u64 v[236:237], s[54:55], 0, v[134:135]
	s_addc_u32 s77, s55, 0
	s_add_i32 s75, s78, s65
	global_load_lds_dwordx4 v[236:237], off
	v_lshl_add_u64 v[238:239], s[76:77], 0, v[130:131]
	s_mov_b32 m0, s75
	v_lshl_add_u64 v[240:241], s[56:57], 0, v[132:133]
	global_load_lds_dwordx4 v[238:239], off
	v_lshl_add_u64 v[238:239], s[76:77], 0, v[134:135]
	s_add_i32 m0, s75, 0x2000
	s_nop 0
	global_load_lds_dwordx4 v[238:239], off
	v_lshl_add_u64 v[238:239], s[56:57], 0, v[128:129]
	s_mov_b32 m0, s15
	s_nop 0
	global_load_lds_dwordx4 v[238:239], off
	s_mov_b32 m0, s17
	s_nop 0
	global_load_lds_dwordx4 v[240:241], off
	s_waitcnt vmcnt(8)
	s_waitcnt lgkmcnt(0)
	s_setprio 1
	s_barrier
; #define PG8_STAGE(bufoff, gbase, voff) do { _Pragma("unroll") for (int _i = 0; _i < 2; ++_i) \
;         __builtin_amdgcn_global_load_lds((const unsigned*)((const char*)(gbase) + (voff)[_i]), (PG8_LAS unsigned*)(lds + (bufoff) + ldsw + _i * 8192), 16, 0, 0); } while (0)
; #define PG8_LDA(dst, b, h) do { _Pragma("unroll") for (int m = 0; m < 4; ++m) _Pragma("unroll") for (int k = 0; k < 2; ++k) dst[m][k] = *(const PG8_LAS bf16x8*)(lds + PG8_SA(b, h) + aoff + m * 2048 + k * 1024); } while (0)
; #define PG8_LDB(dst, b, h) do { _Pragma("unroll") for (int n = 0; n < 2; ++n) _Pragma("unroll") for (int k = 0; k < 2; ++k) dst[n][k] = *(const PG8_LAS bf16x8*)(lds + PG8_SB(b, h) + boff + n * 2048 + k * 1024); } while (0)
; #define PG8_MMA(ai, bj, At, Bt) do { __builtin_amdgcn_s_setprio(1); _Pragma("unroll") for (int m = 0; m < 4; ++m) _Pragma("unroll") for (int n = 0; n < 2; ++n) _Pragma("unroll") for (int k = 0; k < 2; ++k) \
;         acc[ai][bj][m][n] = __builtin_amdgcn_mfma_f32_16x16x32_bf16(Bt[n][k], At[m][k], acc[ai][bj][m][n], 0, 0, 0); __builtin_amdgcn_s_setprio(0); } while (0)
; #define PG8_WAIT_V(n) asm volatile("s_waitcnt vmcnt(" #n ")" ::: "memory")
; #define PG8_WAIT_L(n) asm volatile("s_waitcnt lgkmcnt(" #n ")" ::: "memory")
; #define PG8_BAR __builtin_amdgcn_s_barrier()
; #define PG8_SCHED __builtin_amdgcn_sched_barrier(0)
; template <class Epi, class Sched, bool ALIGN_EPI = false, bool SP2 = false>
; __device__ __forceinline__ void gemm_phase(PG8_LAS unsigned char* lds, const Gemm g, const Sched& S, const Epi& E) {
;     ...
;             PG8_WAIT_V(8); PG8_WAIT_L(0); PG8_BAR; PG8_MMA(1, 0, At, B0); PG8_MMA(1, 1, At, B1); PG8_BAR; PG8_SCHED;
;             PG8_LDB(B0, 1, 0); PG8_LDB(B1, 1, 1); PG8_SCHED; PG8_LDA(At, 1, 0); PG8_STAGE(PG8_SA(0, 1), a2 + hstep, voffA);
;             PG8_WAIT_V(8); PG8_WAIT_L(0); PG8_BAR; PG8_MMA(0, 0, At, B0); PG8_MMA(0, 1, At, B1); PG8_BAR; PG8_SCHED;
	s_waitcnt lgkmcnt(0)
	v_mfma_f32_16x16x32_bf16 v[60:63], v[148:151], v[198:201], v[60:63]
	v_mfma_f32_16x16x32_bf16 v[56:59], v[174:177], v[198:201], v[56:59]
	v_mfma_f32_16x16x32_bf16 v[52:55], v[148:151], v[206:209], v[52:55]
	v_mfma_f32_16x16x32_bf16 v[48:51], v[174:177], v[206:209], v[48:51]
	v_mfma_f32_16x16x32_bf16 v[44:47], v[148:151], v[220:223], v[44:47]
	v_mfma_f32_16x16x32_bf16 v[40:43], v[174:177], v[220:223], v[40:43]
	v_mfma_f32_16x16x32_bf16 v[36:39], v[148:151], v[228:231], v[36:39]
	v_mfma_f32_16x16x32_bf16 v[32:35], v[174:177], v[228:231], v[32:35]
	v_mfma_f32_16x16x32_bf16 v[60:63], v[170:173], v[202:205], v[60:63]
	v_mfma_f32_16x16x32_bf16 v[56:59], v[178:181], v[202:205], v[56:59]
	v_mfma_f32_16x16x32_bf16 v[52:55], v[170:173], v[210:213], v[52:55]
	v_mfma_f32_16x16x32_bf16 v[48:51], v[178:181], v[210:213], v[48:51]
	v_mfma_f32_16x16x32_bf16 v[44:47], v[170:173], v[224:227], v[44:47]
	v_mfma_f32_16x16x32_bf16 v[40:43], v[178:181], v[224:227], v[40:43]
	v_mfma_f32_16x16x32_bf16 v[36:39], v[170:173], v[232:235], v[36:39]
	v_mfma_f32_16x16x32_bf16 v[32:35], v[178:181], v[232:235], v[32:35]
	s_setprio 0
	s_setprio 1
	v_mfma_f32_16x16x32_bf16 v[28:31], v[182:185], v[198:201], v[28:31]
	v_mfma_f32_16x16x32_bf16 v[24:27], v[190:193], v[198:201], v[24:27]
	v_mfma_f32_16x16x32_bf16 v[20:23], v[182:185], v[206:209], v[20:23]
	v_mfma_f32_16x16x32_bf16 v[16:19], v[190:193], v[206:209], v[16:19]
	v_mfma_f32_16x16x32_bf16 v[12:15], v[182:185], v[220:223], v[12:15]
	v_mfma_f32_16x16x32_bf16 v[8:11], v[190:193], v[220:223], v[8:11]
	v_mfma_f32_16x16x32_bf16 v[4:7], v[182:185], v[228:231], v[4:7]
	v_mfma_f32_16x16x32_bf16 v[0:3], v[190:193], v[228:231], v[0:3]
	v_mfma_f32_16x16x32_bf16 v[28:31], v[186:189], v[202:205], v[28:31]
	v_mfma_f32_16x16x32_bf16 v[24:27], v[194:197], v[202:205], v[24:27]
	v_mfma_f32_16x16x32_bf16 v[20:23], v[186:189], v[210:213], v[20:23]
	v_mfma_f32_16x16x32_bf16 v[16:19], v[194:197], v[210:213], v[16:19]
	v_mfma_f32_16x16x32_bf16 v[12:15], v[186:189], v[224:227], v[12:15]
	v_mfma_f32_16x16x32_bf16 v[8:11], v[194:197], v[224:227], v[8:11]
	v_mfma_f32_16x16x32_bf16 v[4:7], v[186:189], v[232:235], v[4:7]
	v_mfma_f32_16x16x32_bf16 v[0:3], v[194:197], v[232:235], v[0:3]
	s_setprio 0
	s_barrier
	s_add_i32 s75, 0, 0x18000
	v_add_u32_e32 v152, s75, v145
	s_add_i32 s76, 0, 0x1c000
	ds_read_b128 v[148:151], v152
	ds_read_b128 v[170:173], v152 offset:1024
	ds_read_b128 v[174:177], v152 offset:2048
	ds_read_b128 v[178:181], v152 offset:3072
	v_add_u32_e32 v152, s76, v145
	ds_read_b128 v[182:185], v152
	ds_read_b128 v[186:189], v152 offset:1024
	ds_read_b128 v[190:193], v152 offset:2048
	ds_read_b128 v[194:197], v152 offset:3072
	s_add_u32 s56, s56, 0x80000
	s_addc_u32 s57, s57, 0
	s_mov_b32 m0, s68
	v_lshl_add_u64 v[242:243], s[56:57], 0, v[128:129]
	ds_read_b128 v[198:201], v147 offset:32768
	ds_read_b128 v[202:205], v147 offset:33792
	ds_read_b128 v[206:209], v147 offset:34816
	ds_read_b128 v[210:213], v147 offset:35840
	ds_read_b128 v[220:223], v147 offset:36864
	ds_read_b128 v[224:227], v147 offset:37888
	ds_read_b128 v[228:231], v147 offset:38912
	ds_read_b128 v[232:235], v147 offset:39936
	global_load_lds_dwordx4 v[242:243], off
	v_lshl_add_u64 v[242:243], s[56:57], 0, v[132:133]
	s_mov_b32 m0, s69
	s_nop 0
	global_load_lds_dwordx4 v[242:243], off
	s_waitcnt vmcnt(8)
	s_waitcnt lgkmcnt(0)
	s_setprio 1
	s_barrier
	s_waitcnt lgkmcnt(0)
	v_mfma_f32_16x16x32_bf16 v[124:127], v[148:151], v[198:201], v[124:127]
	v_mfma_f32_16x16x32_bf16 v[120:123], v[174:177], v[198:201], v[120:123]
	v_mfma_f32_16x16x32_bf16 v[116:119], v[148:151], v[206:209], v[116:119]
	v_mfma_f32_16x16x32_bf16 v[112:115], v[174:177], v[206:209], v[112:115]
	v_mfma_f32_16x16x32_bf16 v[108:111], v[148:151], v[220:223], v[108:111]
	v_mfma_f32_16x16x32_bf16 v[104:107], v[174:177], v[220:223], v[104:107]
	v_mfma_f32_16x16x32_bf16 v[100:103], v[148:151], v[228:231], v[100:103]
	v_mfma_f32_16x16x32_bf16 v[96:99], v[174:177], v[228:231], v[96:99]
	v_mfma_f32_16x16x32_bf16 v[124:127], v[170:173], v[202:205], v[124:127]
	v_mfma_f32_16x16x32_bf16 v[120:123], v[178:181], v[202:205], v[120:123]
	v_mfma_f32_16x16x32_bf16 v[116:119], v[170:173], v[210:213], v[116:119]
	v_mfma_f32_16x16x32_bf16 v[112:115], v[178:181], v[210:213], v[112:115]
	v_mfma_f32_16x16x32_bf16 v[108:111], v[170:173], v[224:227], v[108:111]
	v_mfma_f32_16x16x32_bf16 v[104:107], v[178:181], v[224:227], v[104:107]
	v_mfma_f32_16x16x32_bf16 v[100:103], v[170:173], v[232:235], v[100:103]
	v_mfma_f32_16x16x32_bf16 v[96:99], v[178:181], v[232:235], v[96:99]
	s_setprio 0
	s_setprio 1
	v_mfma_f32_16x16x32_bf16 v[92:95], v[182:185], v[198:201], v[92:95]
	v_mfma_f32_16x16x32_bf16 v[88:91], v[190:193], v[198:201], v[88:91]
	v_mfma_f32_16x16x32_bf16 v[84:87], v[182:185], v[206:209], v[84:87]
	v_mfma_f32_16x16x32_bf16 v[80:83], v[190:193], v[206:209], v[80:83]
	v_mfma_f32_16x16x32_bf16 v[76:79], v[182:185], v[220:223], v[76:79]
	v_mfma_f32_16x16x32_bf16 v[72:75], v[190:193], v[220:223], v[72:75]
	v_mfma_f32_16x16x32_bf16 v[68:71], v[182:185], v[228:231], v[68:71]
	v_mfma_f32_16x16x32_bf16 v[64:67], v[190:193], v[228:231], v[64:67]
	v_mfma_f32_16x16x32_bf16 v[92:95], v[186:189], v[202:205], v[92:95]
	v_mfma_f32_16x16x32_bf16 v[88:91], v[194:197], v[202:205], v[88:91]
	v_mfma_f32_16x16x32_bf16 v[84:87], v[186:189], v[210:213], v[84:87]
	v_mfma_f32_16x16x32_bf16 v[80:83], v[194:197], v[210:213], v[80:83]
	v_mfma_f32_16x16x32_bf16 v[76:79], v[186:189], v[224:227], v[76:79]
	v_mfma_f32_16x16x32_bf16 v[72:75], v[194:197], v[224:227], v[72:75]
	v_mfma_f32_16x16x32_bf16 v[68:71], v[186:189], v[232:235], v[68:71]
	v_mfma_f32_16x16x32_bf16 v[64:67], v[194:197], v[232:235], v[64:67]
	s_setprio 0
	s_barrier
; #define PG8_STAGE(bufoff, gbase, voff) do { _Pragma("unroll") for (int _i = 0; _i < 2; ++_i) \
;         __builtin_amdgcn_global_load_lds((const unsigned*)((const char*)(gbase) + (voff)[_i]), (PG8_LAS unsigned*)(lds + (bufoff) + ldsw + _i * 8192), 16, 0, 0); } while (0)
; #define PG8_LDA(dst, b, h) do { _Pragma("unroll") for (int m = 0; m < 4; ++m) _Pragma("unroll") for (int k = 0; k < 2; ++k) dst[m][k] = *(const PG8_LAS bf16x8*)(lds + PG8_SA(b, h) + aoff + m * 2048 + k * 1024); } while (0)
; #define PG8_MMA(ai, bj, At, Bt) do { __builtin_amdgcn_s_setprio(1); _Pragma("unroll") for (int m = 0; m < 4; ++m) _Pragma("unroll") for (int n = 0; n < 2; ++n) _Pragma("unroll") for (int k = 0; k < 2; ++k) \
;         acc[ai][bj][m][n] = __builtin_amdgcn_mfma_f32_16x16x32_bf16(Bt[n][k], At[m][k], acc[ai][bj][m][n], 0, 0, 0); __builtin_amdgcn_s_setprio(0); } while (0)
; #define PG8_WAIT_V(n) asm volatile("s_waitcnt vmcnt(" #n ")" ::: "memory")
; #define PG8_WAIT_L(n) asm volatile("s_waitcnt lgkmcnt(" #n ")" ::: "memory")
; #define PG8_BAR __builtin_amdgcn_s_barrier()
; #define PG8_SCHED __builtin_amdgcn_sched_barrier(0)
; template <class Epi, class Sched, bool ALIGN_EPI = false, bool SP2 = false>
; __device__ __forceinline__ void gemm_phase(PG8_LAS unsigned char* lds, const Gemm g, const Sched& S, const Epi& E) {
;     ...
;         for (int t = 0; t < nt; t += 2) {
;             const bool last = (t == nt - 2);
;             const char* a1 = cA + (size_t)(t + 1) * kstep;
;             const char* a2 = last ? nA : cA + (size_t)(t + 2) * kstep; const char* b2 = last ? nB : cB + (size_t)(t + 2) * kstep;
;     ...
;             PG8_WAIT_V(8); PG8_WAIT_L(0); PG8_BAR; PG8_MMA(0, 0, At, B0); PG8_MMA(0, 1, At, B1); PG8_BAR; PG8_SCHED;
;             PG8_LDA(At, 1, 1); PG8_STAGE(PG8_SB(1, 0), b3, voffB); PG8_STAGE(PG8_SB(1, 1), b3 + hstep, voffB); PG8_STAGE(PG8_SA(1, 0), a3, voffA);
;             PG8_WAIT_V(8); PG8_WAIT_L(0); PG8_BAR; PG8_MMA(1, 0, At, B0); PG8_MMA(1, 1, At, B1); PG8_BAR; PG8_SCHED;
	s_add_i32 s56, s75, s65
	v_lshl_add_u64 v[214:215], v[214:215], 0, s[90:91]
	s_mov_b32 m0, s56
	ds_read_b128 v[198:201], v147 offset:49152
	ds_read_b128 v[202:205], v147 offset:50176
	ds_read_b128 v[206:209], v147 offset:51200
	ds_read_b128 v[210:213], v147 offset:52224
	ds_read_b128 v[220:223], v147 offset:53248
	ds_read_b128 v[224:227], v147 offset:54272
	ds_read_b128 v[228:231], v147 offset:55296
	ds_read_b128 v[232:235], v147 offset:56320
	global_load_lds_dwordx4 v[214:215], off
	s_add_i32 m0, s56, 0x2000
	s_add_u32 s54, s54, 0x80080
	v_lshl_add_u64 v[214:215], v[236:237], 0, s[90:91]
	s_addc_u32 s55, s55, 0
	s_add_i32 s56, s76, s65
	global_load_lds_dwordx4 v[214:215], off
	v_lshl_add_u64 v[214:215], s[54:55], 0, v[130:131]
	s_mov_b32 m0, s56
	s_nop 0
	global_load_lds_dwordx4 v[214:215], off
	v_lshl_add_u64 v[214:215], s[54:55], 0, v[134:135]
	s_add_i32 m0, s56, 0x2000
	s_nop 0
	global_load_lds_dwordx4 v[214:215], off
	v_lshl_add_u64 v[214:215], v[238:239], 0, s[90:91]
	s_mov_b32 m0, s70
	s_nop 0
	global_load_lds_dwordx4 v[214:215], off
	v_lshl_add_u64 v[214:215], v[240:241], 0, s[90:91]
	s_mov_b32 m0, s71
	s_nop 0
	global_load_lds_dwordx4 v[214:215], off
	s_waitcnt vmcnt(8)
	s_waitcnt lgkmcnt(0)
	s_setprio 1
	s_barrier
	s_waitcnt lgkmcnt(0)
	v_mfma_f32_16x16x32_bf16 v[60:63], v[148:151], v[198:201], v[60:63]
	v_mfma_f32_16x16x32_bf16 v[56:59], v[174:177], v[198:201], v[56:59]
	v_mfma_f32_16x16x32_bf16 v[52:55], v[148:151], v[206:209], v[52:55]
	v_mfma_f32_16x16x32_bf16 v[48:51], v[174:177], v[206:209], v[48:51]
	v_mfma_f32_16x16x32_bf16 v[44:47], v[148:151], v[220:223], v[44:47]
	v_mfma_f32_16x16x32_bf16 v[40:43], v[174:177], v[220:223], v[40:43]
	v_mfma_f32_16x16x32_bf16 v[36:39], v[148:151], v[228:231], v[36:39]
	v_mfma_f32_16x16x32_bf16 v[32:35], v[174:177], v[228:231], v[32:35]
	v_mfma_f32_16x16x32_bf16 v[60:63], v[170:173], v[202:205], v[60:63]
	v_mfma_f32_16x16x32_bf16 v[56:59], v[178:181], v[202:205], v[56:59]
	v_mfma_f32_16x16x32_bf16 v[52:55], v[170:173], v[210:213], v[52:55]
	v_mfma_f32_16x16x32_bf16 v[48:51], v[178:181], v[210:213], v[48:51]
	v_mfma_f32_16x16x32_bf16 v[44:47], v[170:173], v[224:227], v[44:47]
	v_mfma_f32_16x16x32_bf16 v[40:43], v[178:181], v[224:227], v[40:43]
	v_mfma_f32_16x16x32_bf16 v[36:39], v[170:173], v[232:235], v[36:39]
	v_mfma_f32_16x16x32_bf16 v[32:35], v[178:181], v[232:235], v[32:35]
	s_setprio 0
	s_setprio 1
	v_mfma_f32_16x16x32_bf16 v[28:31], v[182:185], v[198:201], v[28:31]
	v_mfma_f32_16x16x32_bf16 v[24:27], v[190:193], v[198:201], v[24:27]
	v_mfma_f32_16x16x32_bf16 v[20:23], v[182:185], v[206:209], v[20:23]
	v_mfma_f32_16x16x32_bf16 v[16:19], v[190:193], v[206:209], v[16:19]
	v_mfma_f32_16x16x32_bf16 v[12:15], v[182:185], v[220:223], v[12:15]
	v_mfma_f32_16x16x32_bf16 v[8:11], v[190:193], v[220:223], v[8:11]
	v_mfma_f32_16x16x32_bf16 v[4:7], v[182:185], v[228:231], v[4:7]
	v_mfma_f32_16x16x32_bf16 v[0:3], v[190:193], v[228:231], v[0:3]
	v_mfma_f32_16x16x32_bf16 v[28:31], v[186:189], v[202:205], v[28:31]
	v_mfma_f32_16x16x32_bf16 v[24:27], v[194:197], v[202:205], v[24:27]
	v_mfma_f32_16x16x32_bf16 v[20:23], v[186:189], v[210:213], v[20:23]
	v_mfma_f32_16x16x32_bf16 v[16:19], v[194:197], v[210:213], v[16:19]
	v_mfma_f32_16x16x32_bf16 v[12:15], v[186:189], v[224:227], v[12:15]
	v_mfma_f32_16x16x32_bf16 v[8:11], v[194:197], v[224:227], v[8:11]
	v_mfma_f32_16x16x32_bf16 v[4:7], v[186:189], v[232:235], v[4:7]
	v_mfma_f32_16x16x32_bf16 v[0:3], v[194:197], v[232:235], v[0:3]
	s_setprio 0
	s_barrier
	s_add_i32 s74, s74, 2
	s_add_u32 s52, s52, 0x100
	s_addc_u32 s53, s53, 0
	s_cmp_gt_u32 s74, 29
	s_cbranch_scc0 .LBB0_431
	s_and_b64 vcc, exec, s[26:27]
	s_cbranch_vccz .LBB0_434
	s_barrier
